# v010 + nt on phase-0 once-read f32 input loads (w_in/w_branch/w_out/x)
# speedup vs baseline: 1.0068x; 1.0056x over previous
; #define LAS __attribute__((address_space(3)))
; __device__ __forceinline__ void transpose_item(const float* W, int ldw, bf16_t* WT, int ldt, int koff, int k0, int nsrc, int ndst, LAS float* scr, int lane) {
;     const float* src = W + (size_t)k0 * ldw + nsrc + lane;
; #pragma unroll 32
;     for (int kk = 0; kk < 64; ++kk) scr[kk * 65 + lane] = src[(size_t)kk * ldw];
; __device__ __forceinline__ void phase0(const Args& a, LAS unsigned char* lds, int bid, int G) {
;     ...
;         if (r < I_IN) { const int kb = r / 384, nb = r - kb * 384; transpose_item(a.w_in, PC, WinT, LDP, 0, 64 * kb, proj_src_col(64 * nb), 64 * nb, scr, lane); continue; } r -= I_IN;
.LBB0_20:
	s_lshl_b32 s9, s77, 6
	s_mul_i32 s10, s77, 0x600000
	s_mul_hi_i32 s9, s9, 0x18000
	s_waitcnt lgkmcnt(0)
	s_add_u32 s10, s40, s10
	s_addc_u32 s11, s41, s9
	s_ashr_i32 s9, s8, 31
	s_lshl_b64 s[8:9], s[8:9], 2
	s_add_u32 s8, s10, s8
	s_addc_u32 s9, s11, s9
	v_lshl_add_u64 v[62:63], s[8:9], 0, v[2:3]
	v_add_co_u32_e32 v4, vcc, s69, v62
	global_load_dword v158, v2, s[8:9] nt
	s_nop 0
	v_addc_co_u32_e32 v5, vcc, 0, v63, vcc
	v_add_co_u32_e32 v6, vcc, s75, v62
	s_mov_b32 s8, 0x108000
	s_nop 0
	v_addc_co_u32_e32 v7, vcc, 0, v63, vcc
	v_add_co_u32_e32 v8, vcc, s88, v62
	s_movk_i32 s10, 0x1000
	s_nop 0
	v_addc_co_u32_e32 v9, vcc, 0, v63, vcc
	v_add_co_u32_e32 v10, vcc, s89, v62
	s_nop 1
	v_addc_co_u32_e32 v11, vcc, 0, v63, vcc
	v_add_co_u32_e32 v12, vcc, s93, v62
	s_nop 1
	v_addc_co_u32_e32 v13, vcc, 0, v63, vcc
	v_add_co_u32_e32 v14, vcc, s27, v62
	s_nop 1
	v_addc_co_u32_e32 v15, vcc, 0, v63, vcc
	v_add_co_u32_e32 v16, vcc, s55, v62
	s_nop 1
	v_addc_co_u32_e32 v17, vcc, 0, v63, vcc
	v_add_co_u32_e32 v18, vcc, s19, v62
	s_nop 1
	v_addc_co_u32_e32 v19, vcc, 0, v63, vcc
	v_add_co_u32_e32 v20, vcc, s35, v62
	s_nop 1
	v_addc_co_u32_e32 v21, vcc, 0, v63, vcc
	v_add_co_u32_e32 v22, vcc, s70, v62
	s_nop 1
	v_addc_co_u32_e32 v23, vcc, 0, v63, vcc
	v_add_co_u32_e32 v24, vcc, s8, v62
	s_mov_b32 s8, 0x120000
	s_nop 0
	v_addc_co_u32_e32 v25, vcc, 0, v63, vcc
	v_add_co_u32_e32 v26, vcc, s8, v62
	s_mov_b32 s8, 0x138000
	s_nop 0
	v_addc_co_u32_e32 v27, vcc, 0, v63, vcc
	v_add_co_u32_e32 v28, vcc, s8, v62
	s_mov_b32 s8, 0x150000
	s_nop 0
	v_addc_co_u32_e32 v29, vcc, 0, v63, vcc
	v_add_co_u32_e32 v30, vcc, s8, v62
	s_mov_b32 s8, 0x168000
	s_nop 0
	v_addc_co_u32_e32 v31, vcc, 0, v63, vcc
	v_add_co_u32_e32 v32, vcc, s8, v62
	s_mov_b32 s8, 0x180000
	s_nop 0
	v_addc_co_u32_e32 v33, vcc, 0, v63, vcc
	v_add_co_u32_e32 v34, vcc, s8, v62
	s_mov_b32 s8, 0x198000
	s_nop 0
	v_addc_co_u32_e32 v35, vcc, 0, v63, vcc
	v_add_co_u32_e32 v36, vcc, s8, v62
	s_mov_b32 s8, 0x1b0000
	s_nop 0
	v_addc_co_u32_e32 v37, vcc, 0, v63, vcc
	v_add_co_u32_e32 v38, vcc, s8, v62
	s_mov_b32 s8, 0x1c8000
	s_nop 0
	v_addc_co_u32_e32 v39, vcc, 0, v63, vcc
	v_add_co_u32_e32 v40, vcc, s8, v62
	s_mov_b32 s8, 0x1e0000
	s_nop 0
	v_addc_co_u32_e32 v41, vcc, 0, v63, vcc
	v_add_co_u32_e32 v42, vcc, s8, v62
	s_mov_b32 s8, 0x1f8000
	s_nop 0
	v_addc_co_u32_e32 v43, vcc, 0, v63, vcc
	v_add_co_u32_e32 v44, vcc, s8, v62
	s_mov_b32 s8, 0x210000
	s_nop 0
	v_addc_co_u32_e32 v45, vcc, 0, v63, vcc
	v_add_co_u32_e32 v46, vcc, s8, v62
	s_mov_b32 s8, 0x228000
	s_nop 0
	v_addc_co_u32_e32 v47, vcc, 0, v63, vcc
	v_add_co_u32_e32 v48, vcc, s8, v62
	s_mov_b32 s8, 0x240000
	s_nop 0
	v_addc_co_u32_e32 v49, vcc, 0, v63, vcc
	v_add_co_u32_e32 v50, vcc, s8, v62
	s_mov_b32 s8, 0x258000
	s_nop 0
	v_addc_co_u32_e32 v51, vcc, 0, v63, vcc
	v_add_co_u32_e32 v52, vcc, s8, v62
	s_mov_b32 s8, 0x270000
	s_nop 0
	v_addc_co_u32_e32 v53, vcc, 0, v63, vcc
	v_add_co_u32_e32 v54, vcc, s8, v62
	s_mov_b32 s8, 0x288000
	s_nop 0
	v_addc_co_u32_e32 v55, vcc, 0, v63, vcc
	v_add_co_u32_e32 v56, vcc, s8, v62
	s_mov_b32 s8, 0x2a0000
	s_nop 0
	v_addc_co_u32_e32 v57, vcc, 0, v63, vcc
	v_add_co_u32_e32 v58, vcc, s8, v62
	s_mov_b32 s8, 0x2b8000
	s_nop 0
	v_addc_co_u32_e32 v59, vcc, 0, v63, vcc
	v_add_co_u32_e32 v60, vcc, s8, v62
	s_mov_b32 s8, 0x2d0000
	s_nop 0
	v_addc_co_u32_e32 v61, vcc, 0, v63, vcc
	v_add_co_u32_e32 v64, vcc, s8, v62
	s_mov_b32 s8, 0x2e8000
	s_nop 0
	v_addc_co_u32_e32 v65, vcc, 0, v63, vcc
	v_add_co_u32_e32 v66, vcc, s8, v62
	s_mov_b32 s8, 0x300000
	s_nop 0
	v_addc_co_u32_e32 v67, vcc, 0, v63, vcc
	v_add_co_u32_e32 v68, vcc, s8, v62
	s_mov_b32 s8, 0x318000
	s_nop 0
	v_addc_co_u32_e32 v69, vcc, 0, v63, vcc
	v_add_co_u32_e32 v70, vcc, s8, v62
	s_mov_b32 s8, 0x330000
	s_nop 0
	v_addc_co_u32_e32 v71, vcc, 0, v63, vcc
	v_add_co_u32_e32 v72, vcc, s8, v62
	s_mov_b32 s8, 0x348000
	s_nop 0
	v_addc_co_u32_e32 v73, vcc, 0, v63, vcc
	v_add_co_u32_e32 v74, vcc, s8, v62
	s_mov_b32 s8, 0x360000
	s_nop 0
	v_addc_co_u32_e32 v75, vcc, 0, v63, vcc
	v_add_co_u32_e32 v76, vcc, s8, v62
	s_mov_b32 s8, 0x378000
	s_nop 0
	v_addc_co_u32_e32 v77, vcc, 0, v63, vcc
	v_add_co_u32_e32 v78, vcc, s8, v62
	s_mov_b32 s8, 0x390000
	s_nop 0
	v_addc_co_u32_e32 v79, vcc, 0, v63, vcc
	v_add_co_u32_e32 v80, vcc, s8, v62
	s_mov_b32 s8, 0x3a8000
	s_nop 0
	v_addc_co_u32_e32 v81, vcc, 0, v63, vcc
	v_add_co_u32_e32 v82, vcc, s8, v62
	s_mov_b32 s8, 0x3c0000
	s_nop 0
	v_addc_co_u32_e32 v83, vcc, 0, v63, vcc
	v_add_co_u32_e32 v84, vcc, s8, v62
	s_mov_b32 s8, 0x3d8000
	s_nop 0
	v_addc_co_u32_e32 v85, vcc, 0, v63, vcc
	v_add_co_u32_e32 v86, vcc, s8, v62
	s_mov_b32 s8, 0x3f0000
	s_nop 0
	v_addc_co_u32_e32 v87, vcc, 0, v63, vcc
	v_add_co_u32_e32 v88, vcc, s8, v62
	s_mov_b32 s8, 0x408000
	s_nop 0
	v_addc_co_u32_e32 v89, vcc, 0, v63, vcc
	v_add_co_u32_e32 v90, vcc, s8, v62
	s_mov_b32 s8, 0x420000
	s_nop 0
	v_addc_co_u32_e32 v91, vcc, 0, v63, vcc
	v_add_co_u32_e32 v92, vcc, s8, v62
	s_mov_b32 s8, 0x438000
	s_nop 0
	v_addc_co_u32_e32 v93, vcc, 0, v63, vcc
	v_add_co_u32_e32 v94, vcc, s8, v62
	s_mov_b32 s8, 0x450000
	s_nop 0
	v_addc_co_u32_e32 v95, vcc, 0, v63, vcc
	v_add_co_u32_e32 v96, vcc, s8, v62
	s_mov_b32 s8, 0x468000
	s_nop 0
	v_addc_co_u32_e32 v97, vcc, 0, v63, vcc
	v_add_co_u32_e32 v98, vcc, s8, v62
	s_mov_b32 s8, 0x480000
	s_nop 0
	v_addc_co_u32_e32 v99, vcc, 0, v63, vcc
	v_add_co_u32_e32 v100, vcc, s8, v62
	s_mov_b32 s8, 0x498000
	s_nop 0
	v_addc_co_u32_e32 v101, vcc, 0, v63, vcc
	v_add_co_u32_e32 v102, vcc, s8, v62
	s_mov_b32 s8, 0x4b0000
	s_nop 0
	v_addc_co_u32_e32 v103, vcc, 0, v63, vcc
	v_add_co_u32_e32 v104, vcc, s8, v62
	s_mov_b32 s8, 0x4c8000
	s_nop 0
; #define LDS_WAIT() asm volatile("s_waitcnt lgkmcnt(0)" ::: "memory")
; __device__ __forceinline__ void transpose_item(const float* W, int ldw, bf16_t* WT, int ldt, int koff, int k0, int nsrc, int ndst, LAS float* scr, int lane) {
;     const float* src = W + (size_t)k0 * ldw + nsrc + lane;
; #pragma unroll 32
;     for (int kk = 0; kk < 64; ++kk) scr[kk * 65 + lane] = src[(size_t)kk * ldw];
;     LDS_WAIT(); asm volatile("" ::: "memory");
	v_addc_co_u32_e32 v105, vcc, 0, v63, vcc
	v_add_co_u32_e32 v106, vcc, s8, v62
	s_mov_b32 s8, 0x4e0000
	s_nop 0
	v_addc_co_u32_e32 v107, vcc, 0, v63, vcc
	v_add_co_u32_e32 v108, vcc, s8, v62
	s_mov_b32 s8, 0x4f8000
	s_nop 0
	v_addc_co_u32_e32 v109, vcc, 0, v63, vcc
	v_add_co_u32_e32 v110, vcc, s8, v62
	s_mov_b32 s8, 0x510000
	s_nop 0
	v_addc_co_u32_e32 v111, vcc, 0, v63, vcc
	v_add_co_u32_e32 v112, vcc, s8, v62
	s_mov_b32 s8, 0x528000
	s_nop 0
	v_addc_co_u32_e32 v113, vcc, 0, v63, vcc
	v_add_co_u32_e32 v114, vcc, s8, v62
	s_mov_b32 s8, 0x540000
	s_nop 0
	v_addc_co_u32_e32 v115, vcc, 0, v63, vcc
	v_add_co_u32_e32 v116, vcc, s8, v62
	s_mov_b32 s8, 0x558000
	s_nop 0
	v_addc_co_u32_e32 v117, vcc, 0, v63, vcc
	v_add_co_u32_e32 v118, vcc, s8, v62
	s_mov_b32 s8, 0x570000
	s_nop 0
	v_addc_co_u32_e32 v119, vcc, 0, v63, vcc
	v_add_co_u32_e32 v120, vcc, s8, v62
	s_mov_b32 s8, 0x588000
	s_nop 0
	v_addc_co_u32_e32 v121, vcc, 0, v63, vcc
	v_add_co_u32_e32 v122, vcc, s8, v62
	s_mov_b32 s8, 0x5a0000
	s_nop 0
	v_addc_co_u32_e32 v123, vcc, 0, v63, vcc
	v_add_co_u32_e32 v124, vcc, s8, v62
	s_mov_b32 s8, 0x5b8000
	s_nop 0
	v_addc_co_u32_e32 v125, vcc, 0, v63, vcc
	v_add_co_u32_e32 v126, vcc, s8, v62
	s_mov_b32 s8, 0x5d0000
	s_nop 0
	v_addc_co_u32_e32 v127, vcc, 0, v63, vcc
	v_add_co_u32_e32 v128, vcc, s8, v62
	s_mov_b32 s8, 0x5e8000
	s_nop 0
	v_addc_co_u32_e32 v129, vcc, 0, v63, vcc
	v_add_co_u32_e32 v62, vcc, s8, v62
	s_mul_i32 s8, s77, 0xffffd000
	s_nop 0
	v_addc_co_u32_e32 v63, vcc, 0, v63, vcc
	global_load_dword v159, v[4:5], off nt
	s_nop 0
	global_load_dword v6, v[6:7], off nt
	s_nop 0
	global_load_dword v7, v[8:9], off nt
	global_load_dword v160, v[10:11], off nt
	s_nop 0
	global_load_dword v12, v[12:13], off nt
	s_nop 0
	global_load_dword v13, v[14:15], off nt
	s_nop 0
	global_load_dword v14, v[16:17], off nt
	global_load_dword v15, v[18:19], off nt
	s_nop 0
	global_load_dword v16, v[20:21], off nt
	global_load_dword v17, v[22:23], off nt
	global_load_dword v18, v[24:25], off nt
	global_load_dword v19, v[26:27], off nt
	s_nop 0
	global_load_dword v20, v[28:29], off nt
	global_load_dword v21, v[30:31], off nt
	global_load_dword v22, v[32:33], off nt
	global_load_dword v23, v[34:35], off nt
	global_load_dword v24, v[36:37], off nt
	global_load_dword v25, v[38:39], off nt
	global_load_dword v26, v[40:41], off nt
	global_load_dword v27, v[42:43], off nt
	global_load_dword v28, v[44:45], off nt
	global_load_dword v29, v[46:47], off nt
	global_load_dword v30, v[48:49], off nt
	global_load_dword v31, v[50:51], off nt
	global_load_dword v32, v[52:53], off nt
	global_load_dword v33, v[54:55], off nt
	global_load_dword v34, v[56:57], off nt
	global_load_dword v35, v[58:59], off nt
	global_load_dword v36, v[60:61], off nt
	global_load_dword v37, v[64:65], off nt
	global_load_dword v38, v[66:67], off nt
	global_load_dword v39, v[68:69], off nt
	global_load_dword v40, v[70:71], off nt
	global_load_dword v41, v[72:73], off nt
	global_load_dword v42, v[74:75], off nt
	global_load_dword v43, v[76:77], off nt
	global_load_dword v44, v[78:79], off nt
	global_load_dword v45, v[80:81], off nt
	global_load_dword v46, v[82:83], off nt
	global_load_dword v47, v[84:85], off nt
	global_load_dword v48, v[86:87], off nt
	global_load_dword v49, v[88:89], off nt
	global_load_dword v50, v[90:91], off nt
	global_load_dword v51, v[92:93], off nt
	global_load_dword v52, v[94:95], off nt
	global_load_dword v53, v[96:97], off nt
	global_load_dword v54, v[98:99], off nt
	global_load_dword v55, v[100:101], off nt
	global_load_dword v56, v[102:103], off nt
	global_load_dword v57, v[104:105], off nt
	global_load_dword v58, v[106:107], off nt
	global_load_dword v59, v[108:109], off nt
	global_load_dword v60, v[110:111], off nt
	global_load_dword v61, v[112:113], off nt
	global_load_dword v64, v[114:115], off nt
	global_load_dword v65, v[116:117], off nt
	global_load_dword v66, v[118:119], off nt
	global_load_dword v67, v[120:121], off nt
	global_load_dword v68, v[122:123], off nt
	global_load_dword v69, v[124:125], off nt
	global_load_dword v70, v[126:127], off nt
	global_load_dword v71, v[128:129], off nt
	s_nop 0
	global_load_dword v62, v[62:63], off nt
	s_add_i32 s8, s23, s8
	s_andn2_b32 s8, s8, 63
	s_waitcnt vmcnt(62)
	ds_write2_b32 v1, v158, v159 offset1:65
	s_waitcnt vmcnt(60)
	ds_write2_b32 v1, v6, v7 offset0:130 offset1:195
	s_waitcnt vmcnt(58)
	ds_write2_b32 v142, v160, v12 offset0:4 offset1:69
	s_waitcnt vmcnt(56)
	ds_write2_b32 v142, v13, v14 offset0:134 offset1:199
	s_waitcnt vmcnt(54)
	ds_write2_b32 v143, v15, v16 offset0:8 offset1:73
	s_waitcnt vmcnt(52)
	ds_write2_b32 v143, v17, v18 offset0:138 offset1:203
	s_waitcnt vmcnt(50)
	ds_write2_b32 v144, v19, v20 offset0:12 offset1:77
	s_waitcnt vmcnt(48)
	ds_write2_b32 v144, v21, v22 offset0:142 offset1:207
	s_waitcnt vmcnt(46)
	ds_write2_b32 v145, v23, v24 offset0:16 offset1:81
	s_waitcnt vmcnt(44)
	ds_write2_b32 v145, v25, v26 offset0:146 offset1:211
	s_waitcnt vmcnt(42)
	ds_write2_b32 v146, v27, v28 offset0:20 offset1:85
	s_waitcnt vmcnt(40)
	ds_write2_b32 v146, v29, v30 offset0:150 offset1:215
	s_waitcnt vmcnt(38)
	ds_write2_b32 v147, v31, v32 offset0:24 offset1:89
	s_waitcnt vmcnt(36)
	ds_write2_b32 v147, v33, v34 offset0:154 offset1:219
	s_waitcnt vmcnt(34)
	ds_write2_b32 v148, v35, v36 offset0:28 offset1:93
	s_waitcnt vmcnt(32)
	ds_write2_b32 v148, v37, v38 offset0:158 offset1:223
	s_waitcnt vmcnt(30)
	ds_write2_b32 v149, v39, v40 offset0:32 offset1:97
	s_waitcnt vmcnt(28)
	ds_write2_b32 v149, v41, v42 offset0:162 offset1:227
	s_waitcnt vmcnt(26)
	ds_write2_b32 v150, v43, v44 offset0:36 offset1:101
	s_waitcnt vmcnt(24)
; #define LAS __attribute__((address_space(3)))
; __device__ __forceinline__ unsigned pk2(float lo, float hi) { return __builtin_bit_cast(unsigned, __builtin_convertvector((f32x2){lo, hi}, bf16x2_t)); }
; #define LDS_WAIT() asm volatile("s_waitcnt lgkmcnt(0)" ::: "memory")
; __device__ __forceinline__ void transpose_item(const float* W, int ldw, bf16_t* WT, int ldt, int koff, int k0, int nsrc, int ndst, LAS float* scr, int lane) {
;     ...
;     for (int kk = 0; kk < 64; ++kk) scr[kk * 65 + lane] = src[(size_t)kk * ldw];
;     LDS_WAIT(); asm volatile("" ::: "memory");
;     const int c = lane & 7;
; #pragma unroll
;     for (int j = 0; j < 8; ++j) { const int n = (lane >> 3) + 8 * j; const LAS float* s = scr + (8 * c) * 65 + n;
;         u32x4 o; o.x = pk2(s[0 * 65], s[1 * 65]); o.y = pk2(s[2 * 65], s[3 * 65]); o.z = pk2(s[4 * 65], s[5 * 65]); o.w = pk2(s[6 * 65], s[7 * 65]);
;         *(u32x4*)((char*)WT + tiled_off_b(ndst + n, koff + k0 + 8 * c)) = o; }
;     LDS_WAIT(); asm volatile("" ::: "memory");
	ds_write2_b32 v150, v45, v46 offset0:166 offset1:231
	s_waitcnt vmcnt(22)
	ds_write2_b32 v151, v47, v48 offset0:40 offset1:105
	s_waitcnt vmcnt(20)
	ds_write2_b32 v151, v49, v50 offset0:170 offset1:235
	s_waitcnt vmcnt(18)
	ds_write2_b32 v152, v51, v52 offset0:44 offset1:109
	s_waitcnt vmcnt(16)
	ds_write2_b32 v152, v53, v54 offset0:174 offset1:239
	s_waitcnt vmcnt(14)
	ds_write2_b32 v153, v55, v56 offset0:48 offset1:113
	s_waitcnt vmcnt(12)
	ds_write2_b32 v153, v57, v58 offset0:178 offset1:243
	s_waitcnt vmcnt(10)
	ds_write2_b32 v154, v59, v60 offset0:52 offset1:117
	s_waitcnt vmcnt(8)
	ds_write2_b32 v154, v61, v64 offset0:182 offset1:247
	s_waitcnt vmcnt(6)
	ds_write2_b32 v155, v65, v66 offset0:56 offset1:121
	s_waitcnt vmcnt(4)
	ds_write2_b32 v155, v67, v68 offset0:186 offset1:251
	s_waitcnt vmcnt(2)
	ds_write2_b32 v156, v69, v70 offset0:60 offset1:125
	s_waitcnt vmcnt(0)
	ds_write2_b32 v156, v71, v62 offset0:190 offset1:255
	s_add_i32 s8, s8, s77
	v_add_u32_e32 v4, s0, v135
	s_waitcnt lgkmcnt(0)
	s_ashr_i32 s9, s8, 31
	v_lshrrev_b32_e32 v4, 3, v4
	s_lshl_b64 s[8:9], s[8:9], 14
	v_and_or_b32 v4, v4, 10, v131
	ds_read2_b32 v[12:13], v134 offset0:65 offset1:73
	ds_read2_b32 v[14:15], v134 offset1:8
	ds_read2_b32 v[16:17], v134 offset0:130 offset1:138
	ds_read2_b32 v[18:19], v134 offset0:195 offset1:203
	ds_read2_b32 v[20:21], v157 offset0:4 offset1:12
	ds_read2_b32 v[22:23], v157 offset0:69 offset1:77
	ds_read2_b32 v[24:25], v157 offset0:134 offset1:142
	ds_read2_b32 v[26:27], v157 offset0:199 offset1:207
	s_add_u32 s8, s14, s8
	v_lshlrev_b32_e32 v63, 10, v4
	s_addc_u32 s9, s15, s9
	v_or_b32_e32 v8, v63, v136
	v_mov_b32_e32 v9, v3
	v_lshl_add_u64 v[4:5], s[8:9], 0, v[8:9]
	v_add_co_u32_e32 v10, vcc, s10, v4
	s_mul_i32 s77, s77, 0xffe80000
	v_add_u32_e32 v72, s0, v140
	v_addc_co_u32_e32 v11, vcc, 0, v5, vcc
	v_add_u32_e32 v9, s77, v141
	s_waitcnt lgkmcnt(6)
	v_cvt_pk_bf16_f32 v4, v14, v12
	s_waitcnt lgkmcnt(4)
	v_cvt_pk_bf16_f32 v5, v16, v18
	s_waitcnt lgkmcnt(2)
	v_cvt_pk_bf16_f32 v6, v20, v22
	s_waitcnt lgkmcnt(0)
	v_cvt_pk_bf16_f32 v7, v24, v26
	v_lshrrev_b32_e32 v12, 3, v72
	global_store_dwordx4 v8, v[4:7], s[8:9]
	v_and_or_b32 v12, v12, 10, v131
	v_lshlrev_b32_e32 v12, 10, v12
	v_cvt_pk_bf16_f32 v4, v15, v13
	v_and_or_b32 v13, v9, s20, v138
	v_lshrrev_b32_e32 v9, 4, v9
	v_and_b32_e32 v9, 32, v9
	v_cvt_pk_bf16_f32 v5, v17, v19
	v_cvt_pk_bf16_f32 v6, v21, v23
	v_cvt_pk_bf16_f32 v7, v25, v27
	v_bitop3_b32 v9, v13, v12, v9 bitop3:0xde
	ds_read2_b32 v[12:13], v134 offset0:16 offset1:24
	ds_read2_b32 v[14:15], v134 offset0:81 offset1:89
	ds_read2_b32 v[16:17], v134 offset0:146 offset1:154
	ds_read2_b32 v[18:19], v134 offset0:211 offset1:219
	ds_read2_b32 v[20:21], v157 offset0:20 offset1:28
	ds_read2_b32 v[22:23], v157 offset0:85 offset1:93
	ds_read2_b32 v[24:25], v157 offset0:150 offset1:158
	ds_read2_b32 v[26:27], v157 offset0:215 offset1:223
	global_store_dwordx4 v9, v[4:7], s[8:9]
	v_xor_b32_e32 v8, 32, v8
	v_mov_b32_e32 v9, v3
	v_add_u32_e32 v28, s0, v133
	s_waitcnt lgkmcnt(6)
	v_cvt_pk_bf16_f32 v4, v12, v14
	s_waitcnt lgkmcnt(4)
	v_cvt_pk_bf16_f32 v5, v16, v18
	s_waitcnt lgkmcnt(2)
	v_cvt_pk_bf16_f32 v6, v20, v22
	s_waitcnt lgkmcnt(0)
	v_cvt_pk_bf16_f32 v7, v24, v26
	v_lshl_add_u64 v[8:9], s[8:9], 0, v[8:9]
	global_store_dwordx4 v[8:9], v[4:7], off offset:512
	v_lshrrev_b32_e32 v8, 3, v28
	v_and_or_b32 v8, v8, 10, v131
	v_cvt_pk_bf16_f32 v4, v13, v15
	v_cvt_pk_bf16_f32 v5, v17, v19
	v_cvt_pk_bf16_f32 v6, v21, v23
	v_cvt_pk_bf16_f32 v7, v25, v27
	ds_read2_b32 v[12:13], v134 offset0:32 offset1:40
	ds_read2_b32 v[14:15], v134 offset0:97 offset1:105
	ds_read2_b32 v[16:17], v134 offset0:162 offset1:170
	ds_read2_b32 v[18:19], v134 offset0:227 offset1:235
	ds_read2_b32 v[20:21], v157 offset0:36 offset1:44
	ds_read2_b32 v[22:23], v157 offset0:101 offset1:109
	ds_read2_b32 v[24:25], v157 offset0:166 offset1:174
	ds_read2_b32 v[26:27], v157 offset0:231 offset1:239
	v_lshlrev_b32_e32 v28, 10, v8
	v_or_b32_e32 v8, v28, v136
	v_xor_b32_e32 v8, 32, v8
	v_mov_b32_e32 v9, v3
	v_lshl_add_u64 v[8:9], s[8:9], 0, v[8:9]
	global_store_dwordx4 v[8:9], v[4:7], off offset:768
	s_movk_i32 s0, 0x1220
	s_waitcnt lgkmcnt(6)
	v_cvt_pk_bf16_f32 v4, v12, v14
	s_waitcnt lgkmcnt(4)
	v_cvt_pk_bf16_f32 v5, v16, v18
	s_waitcnt lgkmcnt(2)
	v_cvt_pk_bf16_f32 v6, v20, v22
	s_waitcnt lgkmcnt(0)
	v_cvt_pk_bf16_f32 v7, v24, v26
	global_store_dwordx4 v[10:11], v[4:7], off
	v_or_b32_e32 v24, v63, v139
	s_nop 0
	v_cvt_pk_bf16_f32 v4, v13, v15
	v_cvt_pk_bf16_f32 v5, v17, v19
	v_cvt_pk_bf16_f32 v6, v21, v23
	ds_read2_b32 v[8:9], v134 offset0:48 offset1:56
	ds_read2_b32 v[10:11], v134 offset0:113 offset1:121
	ds_read2_b32 v[12:13], v134 offset0:178 offset1:186
	ds_read2_b32 v[14:15], v134 offset0:243 offset1:251
	ds_read2_b32 v[16:17], v157 offset0:52 offset1:60
	ds_read2_b32 v[18:19], v157 offset0:117 offset1:125
	ds_read2_b32 v[20:21], v157 offset0:182 offset1:190
	ds_read2_b32 v[22:23], v157 offset0:247 offset1:255
	v_cvt_pk_bf16_f32 v7, v25, v27
	global_store_dwordx4 v24, v[4:7], s[8:9]
	s_waitcnt lgkmcnt(6)
	s_nop 0
	v_cvt_pk_bf16_f32 v4, v8, v10
	s_waitcnt lgkmcnt(4)
	v_cvt_pk_bf16_f32 v5, v12, v14
	s_waitcnt lgkmcnt(2)
	v_cvt_pk_bf16_f32 v6, v16, v18
	s_waitcnt lgkmcnt(0)
	v_cvt_pk_bf16_f32 v7, v20, v22
	v_bitop3_b32 v8, v63, s0, v136 bitop3:0x36
	s_movk_i32 s0, 0x1320
	global_store_dwordx4 v8, v[4:7], s[8:9]
	v_bitop3_b32 v8, v28, s0, v136 bitop3:0x36
	s_nop 0
	v_cvt_pk_bf16_f32 v4, v9, v11
	v_cvt_pk_bf16_f32 v5, v13, v15
	v_cvt_pk_bf16_f32 v6, v17, v19
	v_cvt_pk_bf16_f32 v7, v21, v23
	global_store_dwordx4 v8, v[4:7], s[8:9]
	s_waitcnt lgkmcnt(0)

; #define LAS __attribute__((address_space(3)))
; __device__ __forceinline__ void transpose_item(const float* W, int ldw, bf16_t* WT, int ldt, int koff, int k0, int nsrc, int ndst, LAS float* scr, int lane) {
;     const float* src = W + (size_t)k0 * ldw + nsrc + lane;
; #pragma unroll 32
;     for (int kk = 0; kk < 64; ++kk) scr[kk * 65 + lane] = src[(size_t)kk * ldw];
; __device__ __forceinline__ void phase0(const Args& a, LAS unsigned char* lds, int bid, int G) {
;     ...
;     for (int it = gw; it < NITEMS; it += NGW) {
;         int r = it;
;         if (r < I_IN) { const int kb = r / 384, nb = r - kb * 384; transpose_item(a.w_in, PC, WinT, LDP, 0, 64 * kb, proj_src_col(64 * nb), 64 * nb, scr, lane); continue; } r -= I_IN;
;         if (r < I_B) { const int kb = r >> 6, nb = r & 63; transpose_item(a.w_branch, DM, WbT, LDP, 0, 64 * kb, 64 * nb, 64 * nb, scr, lane); continue; } r -= I_B;
;         if (r < I_B) { const int kb = r >> 6, nb = r & 63; transpose_item(a.w_branch + (size_t)BW * DM, DM, WbT, LDP, BW, 64 * kb, 64 * nb, 64 * nb, scr, lane); continue; } r -= I_B;
;         { const int kb = r >> 6, nb = r & 63; transpose_item(a.w_out, DM, WoT, LDP, 0, 64 * kb, 64 * nb, 64 * nb, scr, lane); }
.LBB0_22:
	s_cmpk_gt_i32 s12, 0x5fff
	s_mov_b64 s[8:9], -1
	s_cbranch_scc0 .LBB0_32
	s_cmpk_gt_u32 s12, 0x67ff
	s_cbranch_scc0 .LBB0_29
	s_and_b32 s10, s25, 0xfc0
	s_cmpk_gt_u32 s12, 0x6fff
	s_cbranch_scc0 .LBB0_26
	s_and_b32 s0, s12, 0x7fffffc0
	s_addk_i32 s0, 0x9000
	v_readlane_b32 s80, v252, 0
	s_lshl_b64 s[8:9], s[0:1], 14
	v_readlane_b32 s84, v252, 4
	v_readlane_b32 s85, v252, 5
	s_add_u32 s8, s84, s8
	s_addc_u32 s9, s85, s9
	s_lshl_b32 s11, s10, 2
	s_add_u32 s8, s8, s11
	s_addc_u32 s9, s9, 0
	v_lshl_add_u64 v[4:5], s[8:9], 0, v[2:3]
	global_load_dword v6, v2, s[8:9] nt
	s_movk_i32 s8, 0x4000
	v_add_co_u32_e32 v8, vcc, s8, v4
	s_mov_b32 s8, 0x8000
	s_nop 0
	v_addc_co_u32_e32 v9, vcc, 0, v5, vcc
	v_add_co_u32_e32 v10, vcc, s8, v4
	s_mov_b32 s8, 0xc000
	s_nop 0
	v_addc_co_u32_e32 v11, vcc, 0, v5, vcc
	v_add_co_u32_e32 v12, vcc, s8, v4
	s_mov_b32 s8, 0x10000
	s_nop 0
	v_addc_co_u32_e32 v13, vcc, 0, v5, vcc
	v_add_co_u32_e32 v14, vcc, s8, v4
	s_mov_b32 s8, 0x14000
	s_nop 0
	v_addc_co_u32_e32 v15, vcc, 0, v5, vcc
	v_add_co_u32_e32 v16, vcc, s8, v4
	s_mov_b32 s8, 0x1c000
	s_nop 0
	v_addc_co_u32_e32 v17, vcc, 0, v5, vcc
	v_add_co_u32_e32 v18, vcc, s69, v4
	s_lshr_b32 s0, s0, 6
	s_nop 0
	v_addc_co_u32_e32 v19, vcc, 0, v5, vcc
	v_add_co_u32_e32 v20, vcc, s8, v4
	s_mov_b32 s8, 0x20000
	s_nop 0
	v_addc_co_u32_e32 v21, vcc, 0, v5, vcc
	v_add_co_u32_e32 v22, vcc, s8, v4
	s_mov_b32 s8, 0x24000
	s_nop 0
	v_addc_co_u32_e32 v23, vcc, 0, v5, vcc
	global_load_dword v7, v[8:9], off nt
	s_nop 0
	global_load_dword v8, v[10:11], off nt
	global_load_dword v9, v[12:13], off nt
	s_nop 0
	global_load_dword v10, v[14:15], off nt
	global_load_dword v11, v[16:17], off nt
	global_load_dword v12, v[18:19], off nt
	global_load_dword v13, v[20:21], off nt
	s_nop 0
	global_load_dword v14, v[22:23], off nt
	v_add_co_u32_e32 v16, vcc, s8, v4
	s_mov_b32 s8, 0x28000
	s_nop 0
	v_addc_co_u32_e32 v17, vcc, 0, v5, vcc
	v_add_co_u32_e32 v18, vcc, s8, v4
	s_mov_b32 s8, 0x2c000
	s_nop 0
	v_addc_co_u32_e32 v19, vcc, 0, v5, vcc
	v_add_co_u32_e32 v20, vcc, s8, v4
	s_mov_b32 s8, 0x34000
	s_nop 0
	v_addc_co_u32_e32 v21, vcc, 0, v5, vcc
	v_add_co_u32_e32 v22, vcc, s75, v4
	v_readlane_b32 s81, v252, 1
	s_nop 0
	v_addc_co_u32_e32 v23, vcc, 0, v5, vcc
	v_add_co_u32_e32 v24, vcc, s8, v4
	s_mov_b32 s8, 0x38000
	s_nop 0
	v_addc_co_u32_e32 v25, vcc, 0, v5, vcc
	v_add_co_u32_e32 v26, vcc, s8, v4
	s_mov_b32 s8, 0x3c000
	s_nop 0
	v_addc_co_u32_e32 v27, vcc, 0, v5, vcc
	v_add_co_u32_e32 v28, vcc, s8, v4
	s_mov_b32 s8, 0x40000
	s_nop 0
	v_addc_co_u32_e32 v29, vcc, 0, v5, vcc
	v_add_co_u32_e32 v30, vcc, s8, v4
	s_mov_b32 s8, 0x44000
	s_nop 0
	v_addc_co_u32_e32 v31, vcc, 0, v5, vcc
	global_load_dword v15, v[16:17], off nt
	s_nop 0
	global_load_dword v16, v[18:19], off nt
	global_load_dword v17, v[20:21], off nt
	s_nop 0
	global_load_dword v18, v[22:23], off nt
	global_load_dword v19, v[24:25], off nt
	global_load_dword v20, v[26:27], off nt
	global_load_dword v21, v[28:29], off nt
	s_nop 0
	global_load_dword v22, v[30:31], off nt
	v_add_co_u32_e32 v24, vcc, s8, v4
	s_mov_b32 s8, 0x4c000
	s_nop 0
	v_addc_co_u32_e32 v25, vcc, 0, v5, vcc
	v_add_co_u32_e32 v26, vcc, s88, v4
	v_readlane_b32 s82, v252, 2
	s_nop 0
	v_addc_co_u32_e32 v27, vcc, 0, v5, vcc
	v_add_co_u32_e32 v28, vcc, s8, v4
	s_mov_b32 s8, 0x50000
	s_nop 0
	v_addc_co_u32_e32 v29, vcc, 0, v5, vcc
	v_add_co_u32_e32 v30, vcc, s8, v4
	s_mov_b32 s8, 0x54000
	s_nop 0
	v_addc_co_u32_e32 v31, vcc, 0, v5, vcc
	v_add_co_u32_e32 v32, vcc, s8, v4
	s_mov_b32 s8, 0x58000
	s_nop 0
	v_addc_co_u32_e32 v33, vcc, 0, v5, vcc
	v_add_co_u32_e32 v34, vcc, s8, v4
	s_mov_b32 s8, 0x5c000
	s_nop 0
	v_addc_co_u32_e32 v35, vcc, 0, v5, vcc
	v_add_co_u32_e32 v36, vcc, s8, v4
	s_mov_b32 s8, 0x64000
	s_nop 0
	v_addc_co_u32_e32 v37, vcc, 0, v5, vcc
	v_add_co_u32_e32 v38, vcc, s89, v4
	v_readlane_b32 s83, v252, 3
	s_nop 0
	v_addc_co_u32_e32 v39, vcc, 0, v5, vcc
	global_load_dword v23, v[24:25], off nt
	global_load_dword v40, v[26:27], off nt
	global_load_dword v41, v[28:29], off nt
	global_load_dword v42, v[30:31], off nt
	global_load_dword v43, v[32:33], off nt
	global_load_dword v44, v[34:35], off nt
	global_load_dword v45, v[36:37], off nt
	global_load_dword v46, v[38:39], off nt
	v_add_co_u32_e32 v24, vcc, s8, v4
	s_mov_b32 s8, 0x68000
	s_nop 0
	v_addc_co_u32_e32 v25, vcc, 0, v5, vcc
	v_add_co_u32_e32 v26, vcc, s8, v4
	s_and_b32 s8, s23, 0x7c0
	s_nop 0
	v_addc_co_u32_e32 v27, vcc, 0, v5, vcc
	v_add_co_u32_e32 v28, vcc, s90, v4
	s_add_i32 s0, s0, s8
	s_nop 0
	v_addc_co_u32_e32 v29, vcc, 0, v5, vcc
	v_add_co_u32_e32 v30, vcc, s91, v4
	s_lshl_b64 s[8:9], s[0:1], 14
	s_nop 0
	v_addc_co_u32_e32 v31, vcc, 0, v5, vcc
	v_add_co_u32_e32 v32, vcc, s92, v4
	v_readlane_b32 s0, v252, 18
	s_nop 0
	v_addc_co_u32_e32 v33, vcc, 0, v5, vcc
	v_add_co_u32_e32 v34, vcc, s93, v4
	s_add_u32 s8, s0, s8
	s_nop 0
	v_addc_co_u32_e32 v35, vcc, 0, v5, vcc
	v_add_co_u32_e32 v36, vcc, s94, v4
	v_readlane_b32 s0, v252, 19
	s_nop 0
	v_addc_co_u32_e32 v37, vcc, 0, v5, vcc
	v_add_co_u32_e32 v38, vcc, s95, v4
	s_addc_u32 s9, s0, s9
	s_nop 0
	v_addc_co_u32_e32 v39, vcc, 0, v5, vcc
	global_load_dword v47, v[24:25], off nt
	global_load_dword v48, v[26:27], off nt
	global_load_dword v49, v[28:29], off nt
	global_load_dword v50, v[30:31], off nt
	global_load_dword v51, v[32:33], off nt
	global_load_dword v52, v[34:35], off nt
	global_load_dword v53, v[36:37], off nt
	global_load_dword v54, v[38:39], off nt
	v_add_co_u32_e32 v24, vcc, s96, v4
	v_readlane_b32 s86, v252, 6
	s_nop 0
	v_addc_co_u32_e32 v25, vcc, 0, v5, vcc
	v_add_co_u32_e32 v26, vcc, s97, v4
	v_readlane_b32 s87, v252, 7
	s_nop 0
; #define LDS_WAIT() asm volatile("s_waitcnt lgkmcnt(0)" ::: "memory")
; __device__ __forceinline__ void transpose_item(const float* W, int ldw, bf16_t* WT, int ldt, int koff, int k0, int nsrc, int ndst, LAS float* scr, int lane) {
;     const float* src = W + (size_t)k0 * ldw + nsrc + lane;
; #pragma unroll 32
;     for (int kk = 0; kk < 64; ++kk) scr[kk * 65 + lane] = src[(size_t)kk * ldw];
;     LDS_WAIT(); asm volatile("" ::: "memory");
	v_addc_co_u32_e32 v27, vcc, 0, v5, vcc
	v_add_co_u32_e32 v28, vcc, s26, v4
	s_nop 1
	v_addc_co_u32_e32 v29, vcc, 0, v5, vcc
	v_add_co_u32_e32 v30, vcc, s27, v4
	s_nop 1
	v_addc_co_u32_e32 v31, vcc, 0, v5, vcc
	v_add_co_u32_e32 v32, vcc, s60, v4
	s_nop 1
	v_addc_co_u32_e32 v33, vcc, 0, v5, vcc
	v_add_co_u32_e32 v34, vcc, s61, v4
	s_nop 1
	v_addc_co_u32_e32 v35, vcc, 0, v5, vcc
	v_add_co_u32_e32 v36, vcc, s52, v4
	s_nop 1
	v_addc_co_u32_e32 v37, vcc, 0, v5, vcc
	v_add_co_u32_e32 v38, vcc, s53, v4
	s_nop 1
	v_addc_co_u32_e32 v39, vcc, 0, v5, vcc
	global_load_dword v55, v[24:25], off nt
	global_load_dword v56, v[26:27], off nt
	global_load_dword v57, v[28:29], off nt
	global_load_dword v58, v[30:31], off nt
	global_load_dword v59, v[32:33], off nt
	global_load_dword v60, v[34:35], off nt
	global_load_dword v61, v[36:37], off nt
	global_load_dword v62, v[38:39], off nt
	v_add_co_u32_e32 v24, vcc, s54, v4
	s_nop 1
	v_addc_co_u32_e32 v25, vcc, 0, v5, vcc
	v_add_co_u32_e32 v26, vcc, s55, v4
	s_nop 1
	v_addc_co_u32_e32 v27, vcc, 0, v5, vcc
	v_add_co_u32_e32 v28, vcc, s56, v4
	s_nop 1
	v_addc_co_u32_e32 v29, vcc, 0, v5, vcc
	v_add_co_u32_e32 v30, vcc, s57, v4
	s_nop 1
	v_addc_co_u32_e32 v31, vcc, 0, v5, vcc
	v_add_co_u32_e32 v32, vcc, s58, v4
	s_nop 1
	v_addc_co_u32_e32 v33, vcc, 0, v5, vcc
	v_add_co_u32_e32 v34, vcc, s59, v4
	s_nop 1
	v_addc_co_u32_e32 v35, vcc, 0, v5, vcc
	v_add_co_u32_e32 v36, vcc, s18, v4
	s_nop 1
	v_addc_co_u32_e32 v37, vcc, 0, v5, vcc
	v_add_co_u32_e32 v38, vcc, s19, v4
	s_nop 1
	v_addc_co_u32_e32 v39, vcc, 0, v5, vcc
	global_load_dword v63, v[24:25], off nt
	global_load_dword v64, v[26:27], off nt
	global_load_dword v65, v[28:29], off nt
	global_load_dword v66, v[30:31], off nt
	global_load_dword v67, v[32:33], off nt
	global_load_dword v68, v[34:35], off nt
	global_load_dword v69, v[36:37], off nt
	global_load_dword v70, v[38:39], off nt
	v_add_co_u32_e32 v24, vcc, s21, v4
	s_nop 1
	v_addc_co_u32_e32 v25, vcc, 0, v5, vcc
	v_add_co_u32_e32 v26, vcc, s22, v4
	s_nop 1
	v_addc_co_u32_e32 v27, vcc, 0, v5, vcc
	v_add_co_u32_e32 v28, vcc, s3, v4
	s_nop 1
	v_addc_co_u32_e32 v29, vcc, 0, v5, vcc
	v_add_co_u32_e32 v30, vcc, s13, v4
	s_nop 1
	v_addc_co_u32_e32 v31, vcc, 0, v5, vcc
	v_add_co_u32_e32 v32, vcc, s34, v4
	s_nop 1
	v_addc_co_u32_e32 v33, vcc, 0, v5, vcc
	v_add_co_u32_e32 v34, vcc, s35, v4
	s_nop 1
	v_addc_co_u32_e32 v35, vcc, 0, v5, vcc
	v_add_co_u32_e32 v36, vcc, s64, v4
	s_nop 1
	v_addc_co_u32_e32 v37, vcc, 0, v5, vcc
	v_add_co_u32_e32 v38, vcc, s65, v4
	s_nop 1
	v_addc_co_u32_e32 v39, vcc, 0, v5, vcc
	global_load_dword v71, v[24:25], off nt
	global_load_dword v72, v[26:27], off nt
	global_load_dword v73, v[28:29], off nt
	global_load_dword v74, v[30:31], off nt
	global_load_dword v75, v[32:33], off nt
	global_load_dword v76, v[34:35], off nt
	s_nop 0
	global_load_dword v36, v[36:37], off nt
	s_nop 0
	global_load_dword v37, v[38:39], off nt
	v_add_co_u32_e32 v24, vcc, s66, v4
	s_nop 1
	v_addc_co_u32_e32 v25, vcc, 0, v5, vcc
	v_add_co_u32_e32 v26, vcc, s67, v4
	s_nop 1
	v_addc_co_u32_e32 v27, vcc, 0, v5, vcc
	v_add_co_u32_e32 v28, vcc, s68, v4
	s_nop 1
	v_addc_co_u32_e32 v29, vcc, 0, v5, vcc
	v_add_co_u32_e32 v30, vcc, s70, v4
	s_nop 1
	v_addc_co_u32_e32 v31, vcc, 0, v5, vcc
	v_add_co_u32_e32 v32, vcc, s71, v4
	s_nop 1
	v_addc_co_u32_e32 v33, vcc, 0, v5, vcc
	v_add_co_u32_e32 v34, vcc, s72, v4
	s_nop 1
	v_addc_co_u32_e32 v35, vcc, 0, v5, vcc
	v_add_co_u32_e32 v4, vcc, s73, v4
	s_nop 1
	v_addc_co_u32_e32 v5, vcc, 0, v5, vcc
	global_load_dword v24, v[24:25], off nt
	s_nop 0
	global_load_dword v25, v[26:27], off nt
	s_nop 0
	global_load_dword v26, v[28:29], off nt
	global_load_dword v27, v[30:31], off nt
	s_nop 0
	global_load_dword v28, v[32:33], off nt
	global_load_dword v29, v[34:35], off nt
	s_nop 0
	global_load_dword v4, v[4:5], off nt
	s_waitcnt vmcnt(62)
	ds_write2_b32 v1, v6, v7 offset1:65
	s_waitcnt vmcnt(60)
	ds_write2_b32 v1, v8, v9 offset0:130 offset1:195
	s_waitcnt vmcnt(58)
	ds_write2_b32 v142, v10, v11 offset0:4 offset1:69
	s_waitcnt vmcnt(56)
	ds_write2_b32 v142, v12, v13 offset0:134 offset1:199
	s_waitcnt vmcnt(54)
	ds_write2_b32 v143, v14, v15 offset0:8 offset1:73
	s_waitcnt vmcnt(52)
	ds_write2_b32 v143, v16, v17 offset0:138 offset1:203
	s_waitcnt vmcnt(50)
	ds_write2_b32 v144, v18, v19 offset0:12 offset1:77
	s_waitcnt vmcnt(48)
	ds_write2_b32 v144, v20, v21 offset0:142 offset1:207
	s_waitcnt vmcnt(46)
	ds_write2_b32 v145, v22, v23 offset0:16 offset1:81
	s_waitcnt vmcnt(44)
	ds_write2_b32 v145, v40, v41 offset0:146 offset1:211
	s_waitcnt vmcnt(42)
	ds_write2_b32 v146, v42, v43 offset0:20 offset1:85
	s_waitcnt vmcnt(40)
	ds_write2_b32 v146, v44, v45 offset0:150 offset1:215
	s_waitcnt vmcnt(38)
	ds_write2_b32 v147, v46, v47 offset0:24 offset1:89
	s_waitcnt vmcnt(36)
	ds_write2_b32 v147, v48, v49 offset0:154 offset1:219
	s_waitcnt vmcnt(34)
	ds_write2_b32 v148, v50, v51 offset0:28 offset1:93
	s_waitcnt vmcnt(32)
	ds_write2_b32 v148, v52, v53 offset0:158 offset1:223
	s_waitcnt vmcnt(30)
	ds_write2_b32 v149, v54, v55 offset0:32 offset1:97
	s_waitcnt vmcnt(28)
	ds_write2_b32 v149, v56, v57 offset0:162 offset1:227
	s_waitcnt vmcnt(26)
	ds_write2_b32 v150, v58, v59 offset0:36 offset1:101
	s_waitcnt vmcnt(24)
	ds_write2_b32 v150, v60, v61 offset0:166 offset1:231
	s_waitcnt vmcnt(22)
	ds_write2_b32 v151, v62, v63 offset0:40 offset1:105
	s_waitcnt vmcnt(20)
	ds_write2_b32 v151, v64, v65 offset0:170 offset1:235
	s_waitcnt vmcnt(18)
	ds_write2_b32 v152, v66, v67 offset0:44 offset1:109
	s_waitcnt vmcnt(16)
	ds_write2_b32 v152, v68, v69 offset0:174 offset1:239
	s_waitcnt vmcnt(14)
; #define LAS __attribute__((address_space(3)))
; __device__ __forceinline__ unsigned pk2(float lo, float hi) { return __builtin_bit_cast(unsigned, __builtin_convertvector((f32x2){lo, hi}, bf16x2_t)); }
; #define LDS_WAIT() asm volatile("s_waitcnt lgkmcnt(0)" ::: "memory")
; __device__ __forceinline__ void transpose_item(const float* W, int ldw, bf16_t* WT, int ldt, int koff, int k0, int nsrc, int ndst, LAS float* scr, int lane) {
;     ...
;     for (int kk = 0; kk < 64; ++kk) scr[kk * 65 + lane] = src[(size_t)kk * ldw];
;     LDS_WAIT(); asm volatile("" ::: "memory");
;     const int c = lane & 7;
; #pragma unroll
;     for (int j = 0; j < 8; ++j) { const int n = (lane >> 3) + 8 * j; const LAS float* s = scr + (8 * c) * 65 + n;
;         u32x4 o; o.x = pk2(s[0 * 65], s[1 * 65]); o.y = pk2(s[2 * 65], s[3 * 65]); o.z = pk2(s[4 * 65], s[5 * 65]); o.w = pk2(s[6 * 65], s[7 * 65]);
;         *(u32x4*)((char*)WT + tiled_off_b(ndst + n, koff + k0 + 8 * c)) = o; }
;     LDS_WAIT(); asm volatile("" ::: "memory");
	ds_write2_b32 v153, v70, v71 offset0:48 offset1:113
	s_waitcnt vmcnt(12)
	ds_write2_b32 v153, v72, v73 offset0:178 offset1:243
	s_waitcnt vmcnt(10)
	ds_write2_b32 v154, v74, v75 offset0:52 offset1:117
	s_waitcnt vmcnt(8)
	ds_write2_b32 v154, v76, v36 offset0:182 offset1:247
	s_waitcnt vmcnt(6)
	ds_write2_b32 v155, v37, v24 offset0:56 offset1:121
	s_waitcnt vmcnt(4)
	ds_write2_b32 v155, v25, v26 offset0:186 offset1:251
	s_waitcnt vmcnt(2)
	ds_write2_b32 v156, v27, v28 offset0:60 offset1:125
	s_waitcnt vmcnt(0)
	ds_write2_b32 v156, v29, v4 offset0:190 offset1:255
	s_waitcnt lgkmcnt(0)
	v_add_u32_e32 v26, s25, v130
	ds_read2_b32 v[8:9], v134 offset0:65 offset1:73
	ds_read2_b32 v[10:11], v134 offset1:8
	ds_read2_b32 v[12:13], v134 offset0:130 offset1:138
	ds_read2_b32 v[14:15], v134 offset0:195 offset1:203
	ds_read2_b32 v[16:17], v157 offset0:4 offset1:12
	ds_read2_b32 v[18:19], v157 offset0:69 offset1:77
	ds_read2_b32 v[20:21], v157 offset0:134 offset1:142
	ds_read2_b32 v[22:23], v157 offset0:199 offset1:207
	v_and_b32_e32 v27, 0xfc3, v26
	s_waitcnt lgkmcnt(0)
	v_cvt_pk_bf16_f32 v4, v10, v8
	v_or_b32_e32 v8, v27, v135
	v_lshrrev_b32_e32 v8, 3, v8
	v_and_or_b32 v8, v8, 10, v131
	v_lshlrev_b32_e32 v10, 6, v26
	v_and_b32_e32 v28, 0xc0, v10
	v_lshlrev_b32_e32 v8, 10, v8
	v_cvt_pk_bf16_f32 v5, v12, v14
	v_cvt_pk_bf16_f32 v6, v16, v18
	v_cvt_pk_bf16_f32 v7, v20, v22
	v_or3_b32 v24, v8, v28, v132
	global_store_dwordx4 v24, v[4:7], s[8:9]
	v_mov_b32_e32 v25, v3
	s_nop 0
	v_cvt_pk_bf16_f32 v4, v11, v9
	v_cvt_pk_bf16_f32 v5, v13, v15
	v_cvt_pk_bf16_f32 v6, v17, v19
	v_cvt_pk_bf16_f32 v7, v21, v23
	ds_read2_b32 v[8:9], v134 offset0:81 offset1:89
	ds_read2_b32 v[10:11], v134 offset0:16 offset1:24
	ds_read2_b32 v[12:13], v134 offset0:146 offset1:154
	ds_read2_b32 v[14:15], v134 offset0:211 offset1:219
	ds_read2_b32 v[16:17], v157 offset0:20 offset1:28
	ds_read2_b32 v[18:19], v157 offset0:85 offset1:93
	ds_read2_b32 v[20:21], v157 offset0:150 offset1:158
	ds_read2_b32 v[22:23], v157 offset0:215 offset1:223
	global_store_dwordx4 v24, v[4:7], s[8:9] offset:256
	v_xor_b32_e32 v24, 32, v24
	v_lshl_add_u64 v[24:25], s[8:9], 0, v[24:25]
	s_waitcnt lgkmcnt(6)
	v_cvt_pk_bf16_f32 v4, v10, v8
	v_or_b32_e32 v8, v27, v133
	v_lshrrev_b32_e32 v8, 3, v8
	v_and_or_b32 v8, v8, 10, v131
	v_lshlrev_b32_e32 v8, 10, v8
	s_waitcnt lgkmcnt(4)
	v_cvt_pk_bf16_f32 v5, v12, v14
	s_waitcnt lgkmcnt(2)
	v_cvt_pk_bf16_f32 v6, v16, v18
	s_waitcnt lgkmcnt(0)
	v_cvt_pk_bf16_f32 v7, v20, v22
	v_or3_b32 v8, v8, v28, v132
	global_store_dwordx4 v[24:25], v[4:7], off offset:512
	v_xor_b32_e32 v8, 32, v8
	s_nop 0
	v_cvt_pk_bf16_f32 v4, v11, v9
	v_mov_b32_e32 v9, v3
	v_cvt_pk_bf16_f32 v5, v13, v15
	v_cvt_pk_bf16_f32 v6, v17, v19
	v_cvt_pk_bf16_f32 v7, v21, v23
	v_lshl_add_u64 v[8:9], s[8:9], 0, v[8:9]
	ds_read2_b32 v[10:11], v134 offset0:32 offset1:40
	ds_read2_b32 v[12:13], v134 offset0:97 offset1:105
	ds_read2_b32 v[14:15], v134 offset0:162 offset1:170
	ds_read2_b32 v[16:17], v134 offset0:227 offset1:235
	ds_read2_b32 v[18:19], v157 offset0:36 offset1:44
	ds_read2_b32 v[20:21], v157 offset0:101 offset1:109
	ds_read2_b32 v[22:23], v157 offset0:166 offset1:174
	ds_read2_b32 v[24:25], v157 offset0:231 offset1:239
	global_store_dwordx4 v[8:9], v[4:7], off offset:768
	v_add_u32_e32 v8, 32, v26
	v_and_or_b32 v9, v8, s74, v135
	v_lshrrev_b32_e32 v9, 3, v9
	v_and_or_b32 v9, v9, 14, v131
	v_lshlrev_b32_e32 v8, 6, v8
	v_and_b32_e32 v8, 0xc0, v8
	v_lshlrev_b32_e32 v9, 10, v9
	s_waitcnt lgkmcnt(6)
	v_cvt_pk_bf16_f32 v4, v10, v12
	s_waitcnt lgkmcnt(4)
	v_cvt_pk_bf16_f32 v5, v14, v16
	s_waitcnt lgkmcnt(2)
	v_cvt_pk_bf16_f32 v6, v18, v20
	s_waitcnt lgkmcnt(0)
	v_cvt_pk_bf16_f32 v7, v22, v24
	v_or3_b32 v8, v9, v8, v132
	global_store_dwordx4 v8, v[4:7], s[8:9]
	v_add_u32_e32 v8, 40, v26
	v_and_or_b32 v9, v8, s74, v135
	v_lshrrev_b32_e32 v9, 3, v9
	v_and_or_b32 v9, v9, 14, v131
	v_lshlrev_b32_e32 v8, 6, v8
	v_and_b32_e32 v8, 0xc0, v8
	v_lshlrev_b32_e32 v9, 10, v9
	v_cvt_pk_bf16_f32 v4, v11, v13
	v_cvt_pk_bf16_f32 v5, v15, v17
	v_cvt_pk_bf16_f32 v6, v19, v21
	v_cvt_pk_bf16_f32 v7, v23, v25
	v_or3_b32 v24, v9, v8, v132
	ds_read2_b32 v[8:9], v134 offset0:48 offset1:56
	ds_read2_b32 v[10:11], v134 offset0:113 offset1:121
	ds_read2_b32 v[12:13], v134 offset0:178 offset1:186
	ds_read2_b32 v[14:15], v134 offset0:243 offset1:251
	ds_read2_b32 v[16:17], v157 offset0:52 offset1:60
	ds_read2_b32 v[18:19], v157 offset0:117 offset1:125
	ds_read2_b32 v[20:21], v157 offset0:182 offset1:190
	ds_read2_b32 v[22:23], v157 offset0:247 offset1:255
	global_store_dwordx4 v24, v[4:7], s[8:9] offset:256
	v_mov_b32_e32 v25, v3
	s_waitcnt lgkmcnt(6)
	v_cvt_pk_bf16_f32 v4, v8, v10
	v_add_u32_e32 v8, 48, v26
	v_and_or_b32 v10, v8, s74, v135
	v_lshrrev_b32_e32 v10, 3, v10
	v_and_or_b32 v10, v10, 14, v131
	v_lshlrev_b32_e32 v8, 6, v8
	v_and_b32_e32 v8, 0xc0, v8
	v_lshlrev_b32_e32 v10, 10, v10
	v_or3_b32 v8, v10, v8, v132
	v_xor_b32_e32 v24, 32, v8
	s_waitcnt lgkmcnt(4)
	v_cvt_pk_bf16_f32 v5, v12, v14
	s_waitcnt lgkmcnt(2)
	v_cvt_pk_bf16_f32 v6, v16, v18
	s_waitcnt lgkmcnt(0)
	v_cvt_pk_bf16_f32 v7, v20, v22
	v_lshl_add_u64 v[24:25], s[8:9], 0, v[24:25]
	v_add_u32_e32 v8, 56, v26
	global_store_dwordx4 v[24:25], v[4:7], off offset:512
	s_nop 1
	v_cvt_pk_bf16_f32 v4, v9, v11
	v_and_or_b32 v9, v8, s74, v133
	v_lshrrev_b32_e32 v9, 3, v9
	v_and_or_b32 v9, v9, 14, v131
	v_lshlrev_b32_e32 v8, 6, v8
	v_and_b32_e32 v8, 0xc0, v8
	v_lshlrev_b32_e32 v9, 10, v9
	v_or3_b32 v8, v9, v8, v132
	v_xor_b32_e32 v8, 32, v8
	v_mov_b32_e32 v9, v3
	v_cvt_pk_bf16_f32 v5, v13, v15
	v_cvt_pk_bf16_f32 v6, v17, v19
	v_cvt_pk_bf16_f32 v7, v21, v23
	v_lshl_add_u64 v[8:9], s[8:9], 0, v[8:9]
	global_store_dwordx4 v[8:9], v[4:7], off offset:768
	s_waitcnt lgkmcnt(0)
	s_mov_b64 s[8:9], 0
; #define LAS __attribute__((address_space(3)))
; __device__ __forceinline__ void transpose_item(const float* W, int ldw, bf16_t* WT, int ldt, int koff, int k0, int nsrc, int ndst, LAS float* scr, int lane) {
;     const float* src = W + (size_t)k0 * ldw + nsrc + lane;
; #pragma unroll 32
;     for (int kk = 0; kk < 64; ++kk) scr[kk * 65 + lane] = src[(size_t)kk * ldw];
; __device__ __forceinline__ void phase0(const Args& a, LAS unsigned char* lds, int bid, int G) {
;     ...
;         if (r < I_B) { const int kb = r >> 6, nb = r & 63; transpose_item(a.w_branch + (size_t)BW * DM, DM, WbT, LDP, BW, 64 * kb, 64 * nb, 64 * nb, scr, lane); continue; } r -= I_B;
.LBB0_26:
	s_andn2_b64 vcc, exec, s[8:9]
	s_cbranch_vccnz .LBB0_28
	s_and_b32 s0, s12, 0x7fc0
	s_addk_i32 s0, 0x9800
	s_lshl_b64 s[8:9], s[0:1], 14
	v_readlane_b32 s0, v252, 20
	s_add_u32 s0, s0, s8
	v_readlane_b32 s8, v252, 21
	s_addc_u32 s9, s8, s9
	s_lshl_b32 s8, s10, 2
	s_add_u32 s8, s0, s8
	s_addc_u32 s9, s9, 0
	v_lshl_add_u64 v[4:5], s[8:9], 0, v[2:3]
	s_movk_i32 s0, 0x4000
	v_add_co_u32_e32 v8, vcc, s0, v4
	s_mov_b32 s0, 0x8000
	s_nop 0
	v_addc_co_u32_e32 v9, vcc, 0, v5, vcc
	v_add_co_u32_e32 v10, vcc, s0, v4
	s_mov_b32 s0, 0xc000
	s_nop 0
	v_addc_co_u32_e32 v11, vcc, 0, v5, vcc
	v_add_co_u32_e32 v12, vcc, s0, v4
	s_mov_b32 s0, 0x10000
	s_nop 0
	v_addc_co_u32_e32 v13, vcc, 0, v5, vcc
	v_add_co_u32_e32 v14, vcc, s0, v4
	s_mov_b32 s0, 0x14000
	s_nop 0
	v_addc_co_u32_e32 v15, vcc, 0, v5, vcc
	v_add_co_u32_e32 v16, vcc, s0, v4
	s_mov_b32 s0, 0x1c000
	s_nop 0
	v_addc_co_u32_e32 v17, vcc, 0, v5, vcc
	v_add_co_u32_e32 v18, vcc, s69, v4
	global_load_dword v6, v2, s[8:9] nt
	s_nop 0
	v_addc_co_u32_e32 v19, vcc, 0, v5, vcc
	v_add_co_u32_e32 v20, vcc, s0, v4
	s_mov_b32 s0, 0x20000
	s_nop 0
	v_addc_co_u32_e32 v21, vcc, 0, v5, vcc
	v_add_co_u32_e32 v22, vcc, s0, v4
	s_mov_b32 s0, 0x24000
	s_nop 0
	v_addc_co_u32_e32 v23, vcc, 0, v5, vcc
	global_load_dword v7, v[8:9], off nt
	s_nop 0
	global_load_dword v8, v[10:11], off nt
	global_load_dword v9, v[12:13], off nt
	s_nop 0
	global_load_dword v10, v[14:15], off nt
	global_load_dword v11, v[16:17], off nt
	global_load_dword v12, v[18:19], off nt
	global_load_dword v13, v[20:21], off nt
	s_nop 0
	global_load_dword v14, v[22:23], off nt
	v_add_co_u32_e32 v16, vcc, s0, v4
	s_mov_b32 s0, 0x28000
	s_nop 0
	v_addc_co_u32_e32 v17, vcc, 0, v5, vcc
	v_add_co_u32_e32 v18, vcc, s0, v4
	s_mov_b32 s0, 0x2c000
	s_nop 0
	v_addc_co_u32_e32 v19, vcc, 0, v5, vcc
	v_add_co_u32_e32 v20, vcc, s0, v4
	s_mov_b32 s0, 0x34000
	s_nop 0
	v_addc_co_u32_e32 v21, vcc, 0, v5, vcc
	v_add_co_u32_e32 v22, vcc, s75, v4
	s_and_b32 s8, s23, 0x7c0
	s_nop 0
	v_addc_co_u32_e32 v23, vcc, 0, v5, vcc
	v_add_co_u32_e32 v24, vcc, s0, v4
	s_mov_b32 s0, 0x38000
	s_nop 0
	v_addc_co_u32_e32 v25, vcc, 0, v5, vcc
	v_add_co_u32_e32 v26, vcc, s0, v4
	s_mov_b32 s0, 0x3c000
	s_nop 0
	v_addc_co_u32_e32 v27, vcc, 0, v5, vcc
	v_add_co_u32_e32 v28, vcc, s0, v4
	s_mov_b32 s0, 0x40000
	s_nop 0
	v_addc_co_u32_e32 v29, vcc, 0, v5, vcc
	v_add_co_u32_e32 v30, vcc, s0, v4
	s_mov_b32 s0, 0x44000
	s_nop 0
	v_addc_co_u32_e32 v31, vcc, 0, v5, vcc
	global_load_dword v15, v[16:17], off nt
	s_nop 0
	global_load_dword v16, v[18:19], off nt
	global_load_dword v17, v[20:21], off nt
	s_nop 0
	global_load_dword v18, v[22:23], off nt
	global_load_dword v19, v[24:25], off nt
	global_load_dword v20, v[26:27], off nt
	global_load_dword v21, v[28:29], off nt
	s_nop 0
	global_load_dword v22, v[30:31], off nt
	v_add_co_u32_e32 v24, vcc, s0, v4
	s_mov_b32 s0, 0x4c000
	s_nop 0
	v_addc_co_u32_e32 v25, vcc, 0, v5, vcc
	v_add_co_u32_e32 v26, vcc, s88, v4
	s_nop 1
	v_addc_co_u32_e32 v27, vcc, 0, v5, vcc
	v_add_co_u32_e32 v28, vcc, s0, v4
	s_mov_b32 s0, 0x50000
	s_nop 0
	v_addc_co_u32_e32 v29, vcc, 0, v5, vcc
	v_add_co_u32_e32 v30, vcc, s0, v4
	s_mov_b32 s0, 0x54000
	s_nop 0
	v_addc_co_u32_e32 v31, vcc, 0, v5, vcc
	v_add_co_u32_e32 v32, vcc, s0, v4
	s_mov_b32 s0, 0x58000
	s_nop 0
	v_addc_co_u32_e32 v33, vcc, 0, v5, vcc
	v_add_co_u32_e32 v34, vcc, s0, v4
	s_mov_b32 s0, 0x5c000
	s_nop 0
	v_addc_co_u32_e32 v35, vcc, 0, v5, vcc
	v_add_co_u32_e32 v36, vcc, s0, v4
	s_mov_b32 s0, 0x64000
	s_nop 0
	v_addc_co_u32_e32 v37, vcc, 0, v5, vcc
	v_add_co_u32_e32 v38, vcc, s89, v4
	s_nop 1
	v_addc_co_u32_e32 v39, vcc, 0, v5, vcc
	global_load_dword v23, v[24:25], off nt
	global_load_dword v40, v[26:27], off nt
	global_load_dword v41, v[28:29], off nt
	global_load_dword v42, v[30:31], off nt
	global_load_dword v43, v[32:33], off nt
	global_load_dword v44, v[34:35], off nt
	global_load_dword v45, v[36:37], off nt
	global_load_dword v46, v[38:39], off nt
	v_add_co_u32_e32 v24, vcc, s0, v4
	s_mov_b32 s0, 0x68000
	s_nop 0
	v_addc_co_u32_e32 v25, vcc, 0, v5, vcc
	v_add_co_u32_e32 v26, vcc, s0, v4
	s_add_i32 s0, s12, 0xffffa000
	s_nop 0
	v_addc_co_u32_e32 v27, vcc, 0, v5, vcc
	v_add_co_u32_e32 v28, vcc, s90, v4
	s_lshr_b32 s0, s0, 6
	s_nop 0
	v_addc_co_u32_e32 v29, vcc, 0, v5, vcc
	v_add_co_u32_e32 v30, vcc, s91, v4
	s_add_i32 s0, s8, s0
	s_nop 0
	v_addc_co_u32_e32 v31, vcc, 0, v5, vcc
	v_add_co_u32_e32 v32, vcc, s92, v4
	s_lshl_b64 s[8:9], s[0:1], 14
	s_nop 0
	v_addc_co_u32_e32 v33, vcc, 0, v5, vcc
	v_add_co_u32_e32 v34, vcc, s93, v4
	s_add_u32 s8, s16, s8
	s_nop 0
	v_addc_co_u32_e32 v35, vcc, 0, v5, vcc
	v_add_co_u32_e32 v36, vcc, s94, v4
	s_addc_u32 s9, s17, s9
	s_nop 0
	v_addc_co_u32_e32 v37, vcc, 0, v5, vcc
	v_add_co_u32_e32 v38, vcc, s95, v4
	s_nop 1
	v_addc_co_u32_e32 v39, vcc, 0, v5, vcc
	global_load_dword v47, v[24:25], off nt
	global_load_dword v48, v[26:27], off nt
	global_load_dword v49, v[28:29], off nt
	global_load_dword v50, v[30:31], off nt
	global_load_dword v51, v[32:33], off nt
	global_load_dword v52, v[34:35], off nt
	global_load_dword v53, v[36:37], off nt
	global_load_dword v54, v[38:39], off nt
	v_add_co_u32_e32 v24, vcc, s96, v4
	s_nop 1
	v_addc_co_u32_e32 v25, vcc, 0, v5, vcc
	v_add_co_u32_e32 v26, vcc, s97, v4
	s_nop 1
	v_addc_co_u32_e32 v27, vcc, 0, v5, vcc
	v_add_co_u32_e32 v28, vcc, s26, v4
	s_nop 1
	v_addc_co_u32_e32 v29, vcc, 0, v5, vcc
	v_add_co_u32_e32 v30, vcc, s27, v4
	s_nop 1
	v_addc_co_u32_e32 v31, vcc, 0, v5, vcc
	v_add_co_u32_e32 v32, vcc, s60, v4
	s_nop 1
	v_addc_co_u32_e32 v33, vcc, 0, v5, vcc
	v_add_co_u32_e32 v34, vcc, s61, v4
	s_nop 1
	v_addc_co_u32_e32 v35, vcc, 0, v5, vcc
; #define LDS_WAIT() asm volatile("s_waitcnt lgkmcnt(0)" ::: "memory")
; __device__ __forceinline__ void transpose_item(const float* W, int ldw, bf16_t* WT, int ldt, int koff, int k0, int nsrc, int ndst, LAS float* scr, int lane) {
;     const float* src = W + (size_t)k0 * ldw + nsrc + lane;
; #pragma unroll 32
;     for (int kk = 0; kk < 64; ++kk) scr[kk * 65 + lane] = src[(size_t)kk * ldw];
;     LDS_WAIT(); asm volatile("" ::: "memory");
	v_add_co_u32_e32 v36, vcc, s52, v4
	s_nop 1
	v_addc_co_u32_e32 v37, vcc, 0, v5, vcc
	v_add_co_u32_e32 v38, vcc, s53, v4
	s_nop 1
	v_addc_co_u32_e32 v39, vcc, 0, v5, vcc
	global_load_dword v55, v[24:25], off nt
	global_load_dword v56, v[26:27], off nt
	global_load_dword v57, v[28:29], off nt
	global_load_dword v58, v[30:31], off nt
	global_load_dword v59, v[32:33], off nt
	global_load_dword v60, v[34:35], off nt
	global_load_dword v61, v[36:37], off nt
	global_load_dword v62, v[38:39], off nt
	v_add_co_u32_e32 v24, vcc, s54, v4
	s_nop 1
	v_addc_co_u32_e32 v25, vcc, 0, v5, vcc
	v_add_co_u32_e32 v26, vcc, s55, v4
	s_nop 1
	v_addc_co_u32_e32 v27, vcc, 0, v5, vcc
	v_add_co_u32_e32 v28, vcc, s56, v4
	s_nop 1
	v_addc_co_u32_e32 v29, vcc, 0, v5, vcc
	v_add_co_u32_e32 v30, vcc, s57, v4
	s_nop 1
	v_addc_co_u32_e32 v31, vcc, 0, v5, vcc
	v_add_co_u32_e32 v32, vcc, s58, v4
	s_nop 1
	v_addc_co_u32_e32 v33, vcc, 0, v5, vcc
	v_add_co_u32_e32 v34, vcc, s59, v4
	s_nop 1
	v_addc_co_u32_e32 v35, vcc, 0, v5, vcc
	v_add_co_u32_e32 v36, vcc, s18, v4
	s_nop 1
	v_addc_co_u32_e32 v37, vcc, 0, v5, vcc
	v_add_co_u32_e32 v38, vcc, s19, v4
	s_nop 1
	v_addc_co_u32_e32 v39, vcc, 0, v5, vcc
	global_load_dword v63, v[24:25], off nt
	global_load_dword v64, v[26:27], off nt
	global_load_dword v65, v[28:29], off nt
	global_load_dword v66, v[30:31], off nt
	global_load_dword v67, v[32:33], off nt
	global_load_dword v68, v[34:35], off nt
	global_load_dword v69, v[36:37], off nt
	global_load_dword v70, v[38:39], off nt
	v_add_co_u32_e32 v24, vcc, s21, v4
	s_nop 1
	v_addc_co_u32_e32 v25, vcc, 0, v5, vcc
	v_add_co_u32_e32 v26, vcc, s22, v4
	s_nop 1
	v_addc_co_u32_e32 v27, vcc, 0, v5, vcc
	v_add_co_u32_e32 v28, vcc, s3, v4
	s_nop 1
	v_addc_co_u32_e32 v29, vcc, 0, v5, vcc
	v_add_co_u32_e32 v30, vcc, s13, v4
	s_nop 1
	v_addc_co_u32_e32 v31, vcc, 0, v5, vcc
	v_add_co_u32_e32 v32, vcc, s34, v4
	s_nop 1
	v_addc_co_u32_e32 v33, vcc, 0, v5, vcc
	v_add_co_u32_e32 v34, vcc, s35, v4
	s_nop 1
	v_addc_co_u32_e32 v35, vcc, 0, v5, vcc
	v_add_co_u32_e32 v36, vcc, s64, v4
	s_nop 1
	v_addc_co_u32_e32 v37, vcc, 0, v5, vcc
	v_add_co_u32_e32 v38, vcc, s65, v4
	s_nop 1
	v_addc_co_u32_e32 v39, vcc, 0, v5, vcc
	global_load_dword v71, v[24:25], off nt
	global_load_dword v72, v[26:27], off nt
	global_load_dword v73, v[28:29], off nt
	global_load_dword v74, v[30:31], off nt
	global_load_dword v75, v[32:33], off nt
	global_load_dword v76, v[34:35], off nt
	s_nop 0
	global_load_dword v36, v[36:37], off nt
	s_nop 0
	global_load_dword v37, v[38:39], off nt
	v_add_co_u32_e32 v24, vcc, s66, v4
	s_nop 1
	v_addc_co_u32_e32 v25, vcc, 0, v5, vcc
	v_add_co_u32_e32 v26, vcc, s67, v4
	s_nop 1
	v_addc_co_u32_e32 v27, vcc, 0, v5, vcc
	v_add_co_u32_e32 v28, vcc, s68, v4
	s_nop 1
	v_addc_co_u32_e32 v29, vcc, 0, v5, vcc
	v_add_co_u32_e32 v30, vcc, s70, v4
	s_nop 1
	v_addc_co_u32_e32 v31, vcc, 0, v5, vcc
	v_add_co_u32_e32 v32, vcc, s71, v4
	s_nop 1
	v_addc_co_u32_e32 v33, vcc, 0, v5, vcc
	v_add_co_u32_e32 v34, vcc, s72, v4
	s_nop 1
	v_addc_co_u32_e32 v35, vcc, 0, v5, vcc
	v_add_co_u32_e32 v4, vcc, s73, v4
	s_nop 1
	v_addc_co_u32_e32 v5, vcc, 0, v5, vcc
	global_load_dword v24, v[24:25], off nt
	s_nop 0
	global_load_dword v25, v[26:27], off nt
	s_nop 0
	global_load_dword v26, v[28:29], off nt
	global_load_dword v27, v[30:31], off nt
	s_nop 0
	global_load_dword v28, v[32:33], off nt
	global_load_dword v29, v[34:35], off nt
	s_nop 0
	global_load_dword v4, v[4:5], off nt
	s_waitcnt vmcnt(62)
	ds_write2_b32 v1, v6, v7 offset1:65
	s_waitcnt vmcnt(60)
	ds_write2_b32 v1, v8, v9 offset0:130 offset1:195
	s_waitcnt vmcnt(58)
	ds_write2_b32 v142, v10, v11 offset0:4 offset1:69
	s_waitcnt vmcnt(56)
	ds_write2_b32 v142, v12, v13 offset0:134 offset1:199
	s_waitcnt vmcnt(54)
	ds_write2_b32 v143, v14, v15 offset0:8 offset1:73
	s_waitcnt vmcnt(52)
	ds_write2_b32 v143, v16, v17 offset0:138 offset1:203
	s_waitcnt vmcnt(50)
	ds_write2_b32 v144, v18, v19 offset0:12 offset1:77
	s_waitcnt vmcnt(48)
	ds_write2_b32 v144, v20, v21 offset0:142 offset1:207
	s_waitcnt vmcnt(46)
	ds_write2_b32 v145, v22, v23 offset0:16 offset1:81
	s_waitcnt vmcnt(44)
	ds_write2_b32 v145, v40, v41 offset0:146 offset1:211
	s_waitcnt vmcnt(42)
	ds_write2_b32 v146, v42, v43 offset0:20 offset1:85
	s_waitcnt vmcnt(40)
	ds_write2_b32 v146, v44, v45 offset0:150 offset1:215
	s_waitcnt vmcnt(38)
	ds_write2_b32 v147, v46, v47 offset0:24 offset1:89
	s_waitcnt vmcnt(36)
	ds_write2_b32 v147, v48, v49 offset0:154 offset1:219
	s_waitcnt vmcnt(34)
	ds_write2_b32 v148, v50, v51 offset0:28 offset1:93
	s_waitcnt vmcnt(32)
	ds_write2_b32 v148, v52, v53 offset0:158 offset1:223
	s_waitcnt vmcnt(30)
	ds_write2_b32 v149, v54, v55 offset0:32 offset1:97
	s_waitcnt vmcnt(28)
	ds_write2_b32 v149, v56, v57 offset0:162 offset1:227
	s_waitcnt vmcnt(26)
	ds_write2_b32 v150, v58, v59 offset0:36 offset1:101
	s_waitcnt vmcnt(24)
	ds_write2_b32 v150, v60, v61 offset0:166 offset1:231
	s_waitcnt vmcnt(22)
	ds_write2_b32 v151, v62, v63 offset0:40 offset1:105
	s_waitcnt vmcnt(20)
	ds_write2_b32 v151, v64, v65 offset0:170 offset1:235
	s_waitcnt vmcnt(18)
	ds_write2_b32 v152, v66, v67 offset0:44 offset1:109
	s_waitcnt vmcnt(16)
	ds_write2_b32 v152, v68, v69 offset0:174 offset1:239
	s_waitcnt vmcnt(14)
	ds_write2_b32 v153, v70, v71 offset0:48 offset1:113
	s_waitcnt vmcnt(12)
	ds_write2_b32 v153, v72, v73 offset0:178 offset1:243
	s_waitcnt vmcnt(10)
	ds_write2_b32 v154, v74, v75 offset0:52 offset1:117
	s_waitcnt vmcnt(8)
; #define LAS __attribute__((address_space(3)))
; __device__ __forceinline__ unsigned pk2(float lo, float hi) { return __builtin_bit_cast(unsigned, __builtin_convertvector((f32x2){lo, hi}, bf16x2_t)); }
; #define LDS_WAIT() asm volatile("s_waitcnt lgkmcnt(0)" ::: "memory")
; __device__ __forceinline__ void transpose_item(const float* W, int ldw, bf16_t* WT, int ldt, int koff, int k0, int nsrc, int ndst, LAS float* scr, int lane) {
;     ...
;     for (int kk = 0; kk < 64; ++kk) scr[kk * 65 + lane] = src[(size_t)kk * ldw];
;     LDS_WAIT(); asm volatile("" ::: "memory");
;     const int c = lane & 7;
; #pragma unroll
;     for (int j = 0; j < 8; ++j) { const int n = (lane >> 3) + 8 * j; const LAS float* s = scr + (8 * c) * 65 + n;
;         u32x4 o; o.x = pk2(s[0 * 65], s[1 * 65]); o.y = pk2(s[2 * 65], s[3 * 65]); o.z = pk2(s[4 * 65], s[5 * 65]); o.w = pk2(s[6 * 65], s[7 * 65]);
;         *(u32x4*)((char*)WT + tiled_off_b(ndst + n, koff + k0 + 8 * c)) = o; }
;     LDS_WAIT(); asm volatile("" ::: "memory");
	ds_write2_b32 v154, v76, v36 offset0:182 offset1:247
	s_waitcnt vmcnt(6)
	ds_write2_b32 v155, v37, v24 offset0:56 offset1:121
	s_waitcnt vmcnt(4)
	ds_write2_b32 v155, v25, v26 offset0:186 offset1:251
	s_waitcnt vmcnt(2)
	ds_write2_b32 v156, v27, v28 offset0:60 offset1:125
	s_waitcnt vmcnt(0)
	ds_write2_b32 v156, v29, v4 offset0:190 offset1:255
	s_waitcnt lgkmcnt(0)
	ds_read2_b32 v[8:9], v134 offset0:65 offset1:73
	ds_read2_b32 v[10:11], v134 offset1:8
	ds_read2_b32 v[12:13], v134 offset0:130 offset1:138
	ds_read2_b32 v[14:15], v134 offset0:195 offset1:203
	ds_read2_b32 v[16:17], v157 offset0:4 offset1:12
	ds_read2_b32 v[18:19], v157 offset0:69 offset1:77
	ds_read2_b32 v[20:21], v157 offset0:134 offset1:142
	ds_read2_b32 v[22:23], v157 offset0:199 offset1:207
	s_waitcnt lgkmcnt(0)
	v_cvt_pk_bf16_f32 v4, v10, v8
	v_add_u32_e32 v8, s25, v135
	v_lshrrev_b32_e32 v8, 3, v8
	v_and_or_b32 v8, v8, 10, v131
	v_lshlrev_b32_e32 v8, 10, v8
	v_cvt_pk_bf16_f32 v5, v12, v14
	v_cvt_pk_bf16_f32 v6, v16, v18
	v_cvt_pk_bf16_f32 v7, v20, v22
	v_or_b32_e32 v24, v8, v136
	global_store_dwordx4 v24, v[4:7], s[8:9]
	v_or_b32_e32 v25, v8, v137
	v_xor_b32_e32 v24, 32, v24
	v_cvt_pk_bf16_f32 v4, v11, v9
	v_cvt_pk_bf16_f32 v5, v13, v15
	v_cvt_pk_bf16_f32 v6, v17, v19
	v_cvt_pk_bf16_f32 v7, v21, v23
	ds_read2_b32 v[8:9], v134 offset0:16 offset1:24
	ds_read2_b32 v[10:11], v134 offset0:81 offset1:89
	ds_read2_b32 v[12:13], v134 offset0:146 offset1:154
	ds_read2_b32 v[14:15], v134 offset0:211 offset1:219
	ds_read2_b32 v[16:17], v157 offset0:20 offset1:28
	ds_read2_b32 v[18:19], v157 offset0:85 offset1:93
	ds_read2_b32 v[20:21], v157 offset0:150 offset1:158
	ds_read2_b32 v[22:23], v157 offset0:215 offset1:223
	global_store_dwordx4 v25, v[4:7], s[8:9]
	v_mov_b32_e32 v25, v3
	v_lshl_add_u64 v[24:25], s[8:9], 0, v[24:25]
	s_waitcnt lgkmcnt(6)
	v_cvt_pk_bf16_f32 v4, v8, v10
	v_add_u32_e32 v8, s25, v133
	v_lshrrev_b32_e32 v8, 3, v8
	v_and_or_b32 v8, v8, 10, v131
	s_waitcnt lgkmcnt(4)
	v_cvt_pk_bf16_f32 v5, v12, v14
	s_waitcnt lgkmcnt(2)
	v_cvt_pk_bf16_f32 v6, v16, v18
	s_waitcnt lgkmcnt(0)
	v_cvt_pk_bf16_f32 v7, v20, v22
	v_lshl_or_b32 v8, v8, 10, v136
	global_store_dwordx4 v[24:25], v[4:7], off offset:512
	v_xor_b32_e32 v8, 32, v8
	v_add_u32_e32 v26, s25, v130
	v_cvt_pk_bf16_f32 v4, v9, v11
	v_mov_b32_e32 v9, v3
	v_cvt_pk_bf16_f32 v5, v13, v15
	v_cvt_pk_bf16_f32 v6, v17, v19
	v_cvt_pk_bf16_f32 v7, v21, v23
	v_lshl_add_u64 v[8:9], s[8:9], 0, v[8:9]
	ds_read2_b32 v[10:11], v134 offset0:32 offset1:40
	ds_read2_b32 v[12:13], v134 offset0:97 offset1:105
	ds_read2_b32 v[14:15], v134 offset0:162 offset1:170
	ds_read2_b32 v[16:17], v134 offset0:227 offset1:235
	ds_read2_b32 v[18:19], v157 offset0:36 offset1:44
	ds_read2_b32 v[20:21], v157 offset0:101 offset1:109
	ds_read2_b32 v[22:23], v157 offset0:166 offset1:174
	ds_read2_b32 v[24:25], v157 offset0:231 offset1:239
	global_store_dwordx4 v[8:9], v[4:7], off offset:768
	v_add_u32_e32 v8, 32, v26
	v_and_or_b32 v9, v8, s74, v135
	v_lshrrev_b32_e32 v9, 3, v9
	v_and_or_b32 v9, v9, 14, v131
	v_lshlrev_b32_e32 v8, 6, v8
	v_and_b32_e32 v8, 0xc0, v8
	v_lshlrev_b32_e32 v9, 10, v9
	s_waitcnt lgkmcnt(6)
	v_cvt_pk_bf16_f32 v4, v10, v12
	s_waitcnt lgkmcnt(4)
	v_cvt_pk_bf16_f32 v5, v14, v16
	s_waitcnt lgkmcnt(2)
	v_cvt_pk_bf16_f32 v6, v18, v20
	s_waitcnt lgkmcnt(0)
	v_cvt_pk_bf16_f32 v7, v22, v24
	v_or3_b32 v8, v9, v8, v132
	global_store_dwordx4 v8, v[4:7], s[8:9]
	v_add_u32_e32 v8, 40, v26
	v_and_or_b32 v9, v8, s74, v135
	v_lshrrev_b32_e32 v9, 3, v9
	v_and_or_b32 v9, v9, 14, v131
	v_lshlrev_b32_e32 v8, 6, v8
	v_and_b32_e32 v8, 0xc0, v8
	v_lshlrev_b32_e32 v9, 10, v9
	v_cvt_pk_bf16_f32 v4, v11, v13
	v_cvt_pk_bf16_f32 v5, v15, v17
	v_cvt_pk_bf16_f32 v6, v19, v21
	v_cvt_pk_bf16_f32 v7, v23, v25
	v_or3_b32 v24, v9, v8, v132
	ds_read2_b32 v[8:9], v134 offset0:48 offset1:56
	ds_read2_b32 v[10:11], v134 offset0:113 offset1:121
	ds_read2_b32 v[12:13], v134 offset0:178 offset1:186
	ds_read2_b32 v[14:15], v134 offset0:243 offset1:251
	ds_read2_b32 v[16:17], v157 offset0:52 offset1:60
	ds_read2_b32 v[18:19], v157 offset0:117 offset1:125
	ds_read2_b32 v[20:21], v157 offset0:182 offset1:190
	ds_read2_b32 v[22:23], v157 offset0:247 offset1:255
	global_store_dwordx4 v24, v[4:7], s[8:9] offset:256
	v_mov_b32_e32 v25, v3
	s_waitcnt lgkmcnt(6)
	v_cvt_pk_bf16_f32 v4, v8, v10
	v_add_u32_e32 v8, 48, v26
	v_and_or_b32 v10, v8, s74, v135
	v_lshrrev_b32_e32 v10, 3, v10
	v_and_or_b32 v10, v10, 14, v131
	v_lshlrev_b32_e32 v8, 6, v8
	v_and_b32_e32 v8, 0xc0, v8
	v_lshlrev_b32_e32 v10, 10, v10
	v_or3_b32 v8, v10, v8, v132
	v_xor_b32_e32 v24, 32, v8
	s_waitcnt lgkmcnt(4)
	v_cvt_pk_bf16_f32 v5, v12, v14
	s_waitcnt lgkmcnt(2)
	v_cvt_pk_bf16_f32 v6, v16, v18
	s_waitcnt lgkmcnt(0)
	v_cvt_pk_bf16_f32 v7, v20, v22
	v_lshl_add_u64 v[24:25], s[8:9], 0, v[24:25]
	v_add_u32_e32 v8, 56, v26
	global_store_dwordx4 v[24:25], v[4:7], off offset:512
	s_nop 1
	v_cvt_pk_bf16_f32 v4, v9, v11
	v_and_or_b32 v9, v8, s74, v133
	v_lshrrev_b32_e32 v9, 3, v9
	v_and_or_b32 v9, v9, 14, v131
	v_lshlrev_b32_e32 v8, 6, v8
	v_and_b32_e32 v8, 0xc0, v8
	v_lshlrev_b32_e32 v9, 10, v9
	v_or3_b32 v8, v9, v8, v132
	v_xor_b32_e32 v8, 32, v8
	v_mov_b32_e32 v9, v3
	v_cvt_pk_bf16_f32 v5, v13, v15
	v_cvt_pk_bf16_f32 v6, v17, v19
	v_cvt_pk_bf16_f32 v7, v21, v23
	v_lshl_add_u64 v[8:9], s[8:9], 0, v[8:9]
	global_store_dwordx4 v[8:9], v[4:7], off offset:768
	s_waitcnt lgkmcnt(0)

; #define LAS __attribute__((address_space(3)))
; __device__ __forceinline__ void transpose_item(const float* W, int ldw, bf16_t* WT, int ldt, int koff, int k0, int nsrc, int ndst, LAS float* scr, int lane) {
;     const float* src = W + (size_t)k0 * ldw + nsrc + lane;
; #pragma unroll 32
;     for (int kk = 0; kk < 64; ++kk) scr[kk * 65 + lane] = src[(size_t)kk * ldw];
; __device__ __forceinline__ void phase0(const Args& a, LAS unsigned char* lds, int bid, int G) {
;     ...
;         if (r < I_B) { const int kb = r >> 6, nb = r & 63; transpose_item(a.w_branch, DM, WbT, LDP, 0, 64 * kb, 64 * nb, 64 * nb, scr, lane); continue; } r -= I_B;
.LBB0_29:
	s_andn2_b64 vcc, exec, s[8:9]
	s_cbranch_vccnz .LBB0_31
	s_and_b32 s0, s12, 0x7fc0
	s_addk_i32 s0, 0xa000
	v_readlane_b32 s80, v252, 0
	s_and_b32 s10, s25, 0xfc0
	s_lshl_b64 s[8:9], s[0:1], 14
	v_readlane_b32 s82, v252, 2
	v_readlane_b32 s83, v252, 3
	s_add_u32 s8, s82, s8
	s_addc_u32 s9, s83, s9
	s_lshl_b32 s10, s10, 2
	s_add_u32 s8, s8, s10
	s_addc_u32 s9, s9, 0
	v_lshl_add_u64 v[4:5], s[8:9], 0, v[2:3]
	global_load_dword v6, v2, s[8:9] nt
	s_movk_i32 s8, 0x4000
	v_add_co_u32_e32 v8, vcc, s8, v4
	s_mov_b32 s8, 0x8000
	s_nop 0
	v_addc_co_u32_e32 v9, vcc, 0, v5, vcc
	v_add_co_u32_e32 v10, vcc, s8, v4
	s_mov_b32 s8, 0xc000
	s_nop 0
	v_addc_co_u32_e32 v11, vcc, 0, v5, vcc
	v_add_co_u32_e32 v12, vcc, s8, v4
	s_mov_b32 s8, 0x10000
	s_nop 0
	v_addc_co_u32_e32 v13, vcc, 0, v5, vcc
	v_add_co_u32_e32 v14, vcc, s8, v4
	s_mov_b32 s8, 0x14000
	s_nop 0
	v_addc_co_u32_e32 v15, vcc, 0, v5, vcc
	v_add_co_u32_e32 v16, vcc, s8, v4
	s_mov_b32 s8, 0x1c000
	s_nop 0
	v_addc_co_u32_e32 v17, vcc, 0, v5, vcc
	v_add_co_u32_e32 v18, vcc, s69, v4
	s_lshr_b32 s0, s0, 6
	s_nop 0
	v_addc_co_u32_e32 v19, vcc, 0, v5, vcc
	v_add_co_u32_e32 v20, vcc, s8, v4
	s_mov_b32 s8, 0x20000
	s_nop 0
	v_addc_co_u32_e32 v21, vcc, 0, v5, vcc
	v_add_co_u32_e32 v22, vcc, s8, v4
	s_mov_b32 s8, 0x24000
	s_nop 0
	v_addc_co_u32_e32 v23, vcc, 0, v5, vcc
	global_load_dword v7, v[8:9], off nt
	s_nop 0
	global_load_dword v8, v[10:11], off nt
	global_load_dword v9, v[12:13], off nt
	s_nop 0
	global_load_dword v10, v[14:15], off nt
	global_load_dword v11, v[16:17], off nt
	global_load_dword v12, v[18:19], off nt
	global_load_dword v13, v[20:21], off nt
	s_nop 0
	global_load_dword v14, v[22:23], off nt
	v_add_co_u32_e32 v16, vcc, s8, v4
	s_mov_b32 s8, 0x28000
	s_nop 0
	v_addc_co_u32_e32 v17, vcc, 0, v5, vcc
	v_add_co_u32_e32 v18, vcc, s8, v4
	s_mov_b32 s8, 0x2c000
	s_nop 0
	v_addc_co_u32_e32 v19, vcc, 0, v5, vcc
	v_add_co_u32_e32 v20, vcc, s8, v4
	s_mov_b32 s8, 0x34000
	s_nop 0
	v_addc_co_u32_e32 v21, vcc, 0, v5, vcc
	v_add_co_u32_e32 v22, vcc, s75, v4
	v_readlane_b32 s81, v252, 1
	s_nop 0
	v_addc_co_u32_e32 v23, vcc, 0, v5, vcc
	v_add_co_u32_e32 v24, vcc, s8, v4
	s_mov_b32 s8, 0x38000
	s_nop 0
	v_addc_co_u32_e32 v25, vcc, 0, v5, vcc
	v_add_co_u32_e32 v26, vcc, s8, v4
	s_mov_b32 s8, 0x3c000
	s_nop 0
	v_addc_co_u32_e32 v27, vcc, 0, v5, vcc
	v_add_co_u32_e32 v28, vcc, s8, v4
	s_mov_b32 s8, 0x40000
	s_nop 0
	v_addc_co_u32_e32 v29, vcc, 0, v5, vcc
	v_add_co_u32_e32 v30, vcc, s8, v4
	s_mov_b32 s8, 0x44000
	s_nop 0
	v_addc_co_u32_e32 v31, vcc, 0, v5, vcc
	global_load_dword v15, v[16:17], off nt
	s_nop 0
	global_load_dword v16, v[18:19], off nt
	global_load_dword v17, v[20:21], off nt
	s_nop 0
	global_load_dword v18, v[22:23], off nt
	global_load_dword v19, v[24:25], off nt
	global_load_dword v20, v[26:27], off nt
	global_load_dword v21, v[28:29], off nt
	s_nop 0
	global_load_dword v22, v[30:31], off nt
	v_add_co_u32_e32 v24, vcc, s8, v4
	s_mov_b32 s8, 0x4c000
	s_nop 0
	v_addc_co_u32_e32 v25, vcc, 0, v5, vcc
	v_add_co_u32_e32 v26, vcc, s88, v4
	v_readlane_b32 s84, v252, 4
	s_nop 0
	v_addc_co_u32_e32 v27, vcc, 0, v5, vcc
	v_add_co_u32_e32 v28, vcc, s8, v4
	s_mov_b32 s8, 0x50000
	s_nop 0
	v_addc_co_u32_e32 v29, vcc, 0, v5, vcc
	v_add_co_u32_e32 v30, vcc, s8, v4
	s_mov_b32 s8, 0x54000
	s_nop 0
	v_addc_co_u32_e32 v31, vcc, 0, v5, vcc
	v_add_co_u32_e32 v32, vcc, s8, v4
	s_mov_b32 s8, 0x58000
	s_nop 0
	v_addc_co_u32_e32 v33, vcc, 0, v5, vcc
	v_add_co_u32_e32 v34, vcc, s8, v4
	s_mov_b32 s8, 0x5c000
	s_nop 0
	v_addc_co_u32_e32 v35, vcc, 0, v5, vcc
	v_add_co_u32_e32 v36, vcc, s8, v4
	s_mov_b32 s8, 0x64000
	s_nop 0
	v_addc_co_u32_e32 v37, vcc, 0, v5, vcc
	v_add_co_u32_e32 v38, vcc, s89, v4
	v_readlane_b32 s85, v252, 5
	s_nop 0
	v_addc_co_u32_e32 v39, vcc, 0, v5, vcc
	global_load_dword v23, v[24:25], off nt
	global_load_dword v40, v[26:27], off nt
	global_load_dword v41, v[28:29], off nt
	global_load_dword v42, v[30:31], off nt
	global_load_dword v43, v[32:33], off nt
	global_load_dword v44, v[34:35], off nt
	global_load_dword v45, v[36:37], off nt
	global_load_dword v46, v[38:39], off nt
	v_add_co_u32_e32 v24, vcc, s8, v4
	s_mov_b32 s8, 0x68000
	s_nop 0
	v_addc_co_u32_e32 v25, vcc, 0, v5, vcc
	v_add_co_u32_e32 v26, vcc, s8, v4
	s_and_b32 s8, s23, 0x7c0
	s_nop 0
	v_addc_co_u32_e32 v27, vcc, 0, v5, vcc
	v_add_co_u32_e32 v28, vcc, s90, v4
	s_add_i32 s0, s0, s8
	s_nop 0
	v_addc_co_u32_e32 v29, vcc, 0, v5, vcc
	v_add_co_u32_e32 v30, vcc, s91, v4
	s_lshl_b64 s[8:9], s[0:1], 14
	s_nop 0
	v_addc_co_u32_e32 v31, vcc, 0, v5, vcc
	v_add_co_u32_e32 v32, vcc, s92, v4
	s_add_u32 s8, s16, s8
	s_nop 0
	v_addc_co_u32_e32 v33, vcc, 0, v5, vcc
	v_add_co_u32_e32 v34, vcc, s93, v4
	s_addc_u32 s9, s17, s9
	s_nop 0
	v_addc_co_u32_e32 v35, vcc, 0, v5, vcc
	v_add_co_u32_e32 v36, vcc, s94, v4
	v_readlane_b32 s86, v252, 6
	s_nop 0
	v_addc_co_u32_e32 v37, vcc, 0, v5, vcc
	v_add_co_u32_e32 v38, vcc, s95, v4
	v_readlane_b32 s87, v252, 7
	s_nop 0
	v_addc_co_u32_e32 v39, vcc, 0, v5, vcc
	global_load_dword v47, v[24:25], off nt
	global_load_dword v48, v[26:27], off nt
	global_load_dword v49, v[28:29], off nt
	global_load_dword v50, v[30:31], off nt
	global_load_dword v51, v[32:33], off nt
	global_load_dword v52, v[34:35], off nt
	global_load_dword v53, v[36:37], off nt
	global_load_dword v54, v[38:39], off nt
	v_add_co_u32_e32 v24, vcc, s96, v4
	s_nop 1
	v_addc_co_u32_e32 v25, vcc, 0, v5, vcc
	v_add_co_u32_e32 v26, vcc, s97, v4
	s_nop 1
	v_addc_co_u32_e32 v27, vcc, 0, v5, vcc
	v_add_co_u32_e32 v28, vcc, s26, v4
	s_nop 1
	v_addc_co_u32_e32 v29, vcc, 0, v5, vcc
	v_add_co_u32_e32 v30, vcc, s27, v4
	s_nop 1
	v_addc_co_u32_e32 v31, vcc, 0, v5, vcc
; #define LDS_WAIT() asm volatile("s_waitcnt lgkmcnt(0)" ::: "memory")
; __device__ __forceinline__ void transpose_item(const float* W, int ldw, bf16_t* WT, int ldt, int koff, int k0, int nsrc, int ndst, LAS float* scr, int lane) {
;     const float* src = W + (size_t)k0 * ldw + nsrc + lane;
; #pragma unroll 32
;     for (int kk = 0; kk < 64; ++kk) scr[kk * 65 + lane] = src[(size_t)kk * ldw];
;     LDS_WAIT(); asm volatile("" ::: "memory");
	v_add_co_u32_e32 v32, vcc, s60, v4
	s_nop 1
	v_addc_co_u32_e32 v33, vcc, 0, v5, vcc
	v_add_co_u32_e32 v34, vcc, s61, v4
	s_nop 1
	v_addc_co_u32_e32 v35, vcc, 0, v5, vcc
	v_add_co_u32_e32 v36, vcc, s52, v4
	s_nop 1
	v_addc_co_u32_e32 v37, vcc, 0, v5, vcc
	v_add_co_u32_e32 v38, vcc, s53, v4
	s_nop 1
	v_addc_co_u32_e32 v39, vcc, 0, v5, vcc
	global_load_dword v55, v[24:25], off nt
	global_load_dword v56, v[26:27], off nt
	global_load_dword v57, v[28:29], off nt
	global_load_dword v58, v[30:31], off nt
	global_load_dword v59, v[32:33], off nt
	global_load_dword v60, v[34:35], off nt
	global_load_dword v61, v[36:37], off nt
	global_load_dword v62, v[38:39], off nt
	v_add_co_u32_e32 v24, vcc, s54, v4
	s_nop 1
	v_addc_co_u32_e32 v25, vcc, 0, v5, vcc
	v_add_co_u32_e32 v26, vcc, s55, v4
	s_nop 1
	v_addc_co_u32_e32 v27, vcc, 0, v5, vcc
	v_add_co_u32_e32 v28, vcc, s56, v4
	s_nop 1
	v_addc_co_u32_e32 v29, vcc, 0, v5, vcc
	v_add_co_u32_e32 v30, vcc, s57, v4
	s_nop 1
	v_addc_co_u32_e32 v31, vcc, 0, v5, vcc
	v_add_co_u32_e32 v32, vcc, s58, v4
	s_nop 1
	v_addc_co_u32_e32 v33, vcc, 0, v5, vcc
	v_add_co_u32_e32 v34, vcc, s59, v4
	s_nop 1
	v_addc_co_u32_e32 v35, vcc, 0, v5, vcc
	v_add_co_u32_e32 v36, vcc, s18, v4
	s_nop 1
	v_addc_co_u32_e32 v37, vcc, 0, v5, vcc
	v_add_co_u32_e32 v38, vcc, s19, v4
	s_nop 1
	v_addc_co_u32_e32 v39, vcc, 0, v5, vcc
	global_load_dword v63, v[24:25], off nt
	global_load_dword v64, v[26:27], off nt
	global_load_dword v65, v[28:29], off nt
	global_load_dword v66, v[30:31], off nt
	global_load_dword v67, v[32:33], off nt
	global_load_dword v68, v[34:35], off nt
	global_load_dword v69, v[36:37], off nt
	global_load_dword v70, v[38:39], off nt
	v_add_co_u32_e32 v24, vcc, s21, v4
	s_nop 1
	v_addc_co_u32_e32 v25, vcc, 0, v5, vcc
	v_add_co_u32_e32 v26, vcc, s22, v4
	s_nop 1
	v_addc_co_u32_e32 v27, vcc, 0, v5, vcc
	v_add_co_u32_e32 v28, vcc, s3, v4
	s_nop 1
	v_addc_co_u32_e32 v29, vcc, 0, v5, vcc
	v_add_co_u32_e32 v30, vcc, s13, v4
	s_nop 1
	v_addc_co_u32_e32 v31, vcc, 0, v5, vcc
	v_add_co_u32_e32 v32, vcc, s34, v4
	s_nop 1
	v_addc_co_u32_e32 v33, vcc, 0, v5, vcc
	v_add_co_u32_e32 v34, vcc, s35, v4
	s_nop 1
	v_addc_co_u32_e32 v35, vcc, 0, v5, vcc
	v_add_co_u32_e32 v36, vcc, s64, v4
	s_nop 1
	v_addc_co_u32_e32 v37, vcc, 0, v5, vcc
	v_add_co_u32_e32 v38, vcc, s65, v4
	s_nop 1
	v_addc_co_u32_e32 v39, vcc, 0, v5, vcc
	global_load_dword v71, v[24:25], off nt
	global_load_dword v72, v[26:27], off nt
	global_load_dword v73, v[28:29], off nt
	global_load_dword v74, v[30:31], off nt
	global_load_dword v75, v[32:33], off nt
	global_load_dword v76, v[34:35], off nt
	s_nop 0
	global_load_dword v36, v[36:37], off nt
	s_nop 0
	global_load_dword v37, v[38:39], off nt
	v_add_co_u32_e32 v24, vcc, s66, v4
	s_nop 1
	v_addc_co_u32_e32 v25, vcc, 0, v5, vcc
	v_add_co_u32_e32 v26, vcc, s67, v4
	s_nop 1
	v_addc_co_u32_e32 v27, vcc, 0, v5, vcc
	v_add_co_u32_e32 v28, vcc, s68, v4
	s_nop 1
	v_addc_co_u32_e32 v29, vcc, 0, v5, vcc
	v_add_co_u32_e32 v30, vcc, s70, v4
	s_nop 1
	v_addc_co_u32_e32 v31, vcc, 0, v5, vcc
	v_add_co_u32_e32 v32, vcc, s71, v4
	s_nop 1
	v_addc_co_u32_e32 v33, vcc, 0, v5, vcc
	v_add_co_u32_e32 v34, vcc, s72, v4
	s_nop 1
	v_addc_co_u32_e32 v35, vcc, 0, v5, vcc
	v_add_co_u32_e32 v4, vcc, s73, v4
	s_nop 1
	v_addc_co_u32_e32 v5, vcc, 0, v5, vcc
	global_load_dword v24, v[24:25], off nt
	s_nop 0
	global_load_dword v25, v[26:27], off nt
	s_nop 0
	global_load_dword v26, v[28:29], off nt
	global_load_dword v27, v[30:31], off nt
	s_nop 0
	global_load_dword v28, v[32:33], off nt
	global_load_dword v29, v[34:35], off nt
	s_nop 0
	global_load_dword v4, v[4:5], off nt
	s_waitcnt vmcnt(62)
	ds_write2_b32 v1, v6, v7 offset1:65
	s_waitcnt vmcnt(60)
	ds_write2_b32 v1, v8, v9 offset0:130 offset1:195
	s_waitcnt vmcnt(58)
	ds_write2_b32 v142, v10, v11 offset0:4 offset1:69
	s_waitcnt vmcnt(56)
	ds_write2_b32 v142, v12, v13 offset0:134 offset1:199
	s_waitcnt vmcnt(54)
	ds_write2_b32 v143, v14, v15 offset0:8 offset1:73
	s_waitcnt vmcnt(52)
	ds_write2_b32 v143, v16, v17 offset0:138 offset1:203
	s_waitcnt vmcnt(50)
	ds_write2_b32 v144, v18, v19 offset0:12 offset1:77
	s_waitcnt vmcnt(48)
	ds_write2_b32 v144, v20, v21 offset0:142 offset1:207
	s_waitcnt vmcnt(46)
	ds_write2_b32 v145, v22, v23 offset0:16 offset1:81
	s_waitcnt vmcnt(44)
	ds_write2_b32 v145, v40, v41 offset0:146 offset1:211
	s_waitcnt vmcnt(42)
	ds_write2_b32 v146, v42, v43 offset0:20 offset1:85
	s_waitcnt vmcnt(40)
	ds_write2_b32 v146, v44, v45 offset0:150 offset1:215
	s_waitcnt vmcnt(38)
	ds_write2_b32 v147, v46, v47 offset0:24 offset1:89
	s_waitcnt vmcnt(36)
	ds_write2_b32 v147, v48, v49 offset0:154 offset1:219
	s_waitcnt vmcnt(34)
	ds_write2_b32 v148, v50, v51 offset0:28 offset1:93
	s_waitcnt vmcnt(32)
	ds_write2_b32 v148, v52, v53 offset0:158 offset1:223
	s_waitcnt vmcnt(30)
	ds_write2_b32 v149, v54, v55 offset0:32 offset1:97
	s_waitcnt vmcnt(28)
	ds_write2_b32 v149, v56, v57 offset0:162 offset1:227
	s_waitcnt vmcnt(26)
	ds_write2_b32 v150, v58, v59 offset0:36 offset1:101
	s_waitcnt vmcnt(24)
	ds_write2_b32 v150, v60, v61 offset0:166 offset1:231
	s_waitcnt vmcnt(22)
	ds_write2_b32 v151, v62, v63 offset0:40 offset1:105
	s_waitcnt vmcnt(20)
	ds_write2_b32 v151, v64, v65 offset0:170 offset1:235
	s_waitcnt vmcnt(18)
	ds_write2_b32 v152, v66, v67 offset0:44 offset1:109
	s_waitcnt vmcnt(16)
	ds_write2_b32 v152, v68, v69 offset0:174 offset1:239
	s_waitcnt vmcnt(14)
	ds_write2_b32 v153, v70, v71 offset0:48 offset1:113
	s_waitcnt vmcnt(12)
; #define LAS __attribute__((address_space(3)))
; __device__ __forceinline__ unsigned pk2(float lo, float hi) { return __builtin_bit_cast(unsigned, __builtin_convertvector((f32x2){lo, hi}, bf16x2_t)); }
; #define LDS_WAIT() asm volatile("s_waitcnt lgkmcnt(0)" ::: "memory")
; __device__ __forceinline__ void transpose_item(const float* W, int ldw, bf16_t* WT, int ldt, int koff, int k0, int nsrc, int ndst, LAS float* scr, int lane) {
;     ...
;     for (int kk = 0; kk < 64; ++kk) scr[kk * 65 + lane] = src[(size_t)kk * ldw];
;     LDS_WAIT(); asm volatile("" ::: "memory");
;     const int c = lane & 7;
; #pragma unroll
;     for (int j = 0; j < 8; ++j) { const int n = (lane >> 3) + 8 * j; const LAS float* s = scr + (8 * c) * 65 + n;
;         u32x4 o; o.x = pk2(s[0 * 65], s[1 * 65]); o.y = pk2(s[2 * 65], s[3 * 65]); o.z = pk2(s[4 * 65], s[5 * 65]); o.w = pk2(s[6 * 65], s[7 * 65]);
;         *(u32x4*)((char*)WT + tiled_off_b(ndst + n, koff + k0 + 8 * c)) = o; }
;     LDS_WAIT(); asm volatile("" ::: "memory");
	ds_write2_b32 v153, v72, v73 offset0:178 offset1:243
	s_waitcnt vmcnt(10)
	ds_write2_b32 v154, v74, v75 offset0:52 offset1:117
	s_waitcnt vmcnt(8)
	ds_write2_b32 v154, v76, v36 offset0:182 offset1:247
	s_waitcnt vmcnt(6)
	ds_write2_b32 v155, v37, v24 offset0:56 offset1:121
	s_waitcnt vmcnt(4)
	ds_write2_b32 v155, v25, v26 offset0:186 offset1:251
	s_waitcnt vmcnt(2)
	ds_write2_b32 v156, v27, v28 offset0:60 offset1:125
	s_waitcnt vmcnt(0)
	ds_write2_b32 v156, v29, v4 offset0:190 offset1:255
	s_waitcnt lgkmcnt(0)
	ds_read2_b32 v[8:9], v134 offset0:65 offset1:73
	ds_read2_b32 v[10:11], v134 offset1:8
	ds_read2_b32 v[12:13], v134 offset0:130 offset1:138
	ds_read2_b32 v[14:15], v134 offset0:195 offset1:203
	ds_read2_b32 v[16:17], v157 offset0:4 offset1:12
	ds_read2_b32 v[18:19], v157 offset0:69 offset1:77
	ds_read2_b32 v[20:21], v157 offset0:134 offset1:142
	ds_read2_b32 v[22:23], v157 offset0:199 offset1:207
	s_waitcnt lgkmcnt(0)
	v_cvt_pk_bf16_f32 v4, v10, v8
	v_add_u32_e32 v8, s25, v135
	v_lshrrev_b32_e32 v8, 3, v8
	v_and_or_b32 v8, v8, 10, v131
	v_lshlrev_b32_e32 v8, 10, v8
	v_cvt_pk_bf16_f32 v5, v12, v14
	v_cvt_pk_bf16_f32 v6, v16, v18
	v_cvt_pk_bf16_f32 v7, v20, v22
	v_or_b32_e32 v24, v8, v136
	global_store_dwordx4 v24, v[4:7], s[8:9]
	v_or_b32_e32 v25, v8, v137
	v_xor_b32_e32 v24, 32, v24
	v_cvt_pk_bf16_f32 v4, v11, v9
	v_cvt_pk_bf16_f32 v5, v13, v15
	v_cvt_pk_bf16_f32 v6, v17, v19
	v_cvt_pk_bf16_f32 v7, v21, v23
	ds_read2_b32 v[8:9], v134 offset0:16 offset1:24
	ds_read2_b32 v[10:11], v134 offset0:81 offset1:89
	ds_read2_b32 v[12:13], v134 offset0:146 offset1:154
	ds_read2_b32 v[14:15], v134 offset0:211 offset1:219
	ds_read2_b32 v[16:17], v157 offset0:20 offset1:28
	ds_read2_b32 v[18:19], v157 offset0:85 offset1:93
	ds_read2_b32 v[20:21], v157 offset0:150 offset1:158
	ds_read2_b32 v[22:23], v157 offset0:215 offset1:223
	global_store_dwordx4 v25, v[4:7], s[8:9]
	v_mov_b32_e32 v25, v3
	v_lshl_add_u64 v[24:25], s[8:9], 0, v[24:25]
	s_waitcnt lgkmcnt(6)
	v_cvt_pk_bf16_f32 v4, v8, v10
	v_add_u32_e32 v8, s25, v133
	v_lshrrev_b32_e32 v8, 3, v8
	v_and_or_b32 v8, v8, 10, v131
	s_waitcnt lgkmcnt(4)
	v_cvt_pk_bf16_f32 v5, v12, v14
	s_waitcnt lgkmcnt(2)
	v_cvt_pk_bf16_f32 v6, v16, v18
	s_waitcnt lgkmcnt(0)
	v_cvt_pk_bf16_f32 v7, v20, v22
	v_lshl_or_b32 v8, v8, 10, v136
	global_store_dwordx4 v[24:25], v[4:7], off offset:512
	v_xor_b32_e32 v8, 32, v8
	v_add_u32_e32 v26, s25, v130
	v_cvt_pk_bf16_f32 v4, v9, v11
	v_mov_b32_e32 v9, v3
	v_cvt_pk_bf16_f32 v5, v13, v15
	v_cvt_pk_bf16_f32 v6, v17, v19
	v_cvt_pk_bf16_f32 v7, v21, v23
	v_lshl_add_u64 v[8:9], s[8:9], 0, v[8:9]
	ds_read2_b32 v[10:11], v134 offset0:32 offset1:40
	ds_read2_b32 v[12:13], v134 offset0:97 offset1:105
	ds_read2_b32 v[14:15], v134 offset0:162 offset1:170
	ds_read2_b32 v[16:17], v134 offset0:227 offset1:235
	ds_read2_b32 v[18:19], v157 offset0:36 offset1:44
	ds_read2_b32 v[20:21], v157 offset0:101 offset1:109
	ds_read2_b32 v[22:23], v157 offset0:166 offset1:174
	ds_read2_b32 v[24:25], v157 offset0:231 offset1:239
	global_store_dwordx4 v[8:9], v[4:7], off offset:768
	v_add_u32_e32 v8, 32, v26
	v_and_or_b32 v9, v8, s74, v135
	v_lshrrev_b32_e32 v9, 3, v9
	v_and_or_b32 v9, v9, 14, v131
	v_lshlrev_b32_e32 v8, 6, v8
	v_and_b32_e32 v8, 0xc0, v8
	v_lshlrev_b32_e32 v9, 10, v9
	s_waitcnt lgkmcnt(6)
	v_cvt_pk_bf16_f32 v4, v10, v12
	s_waitcnt lgkmcnt(4)
	v_cvt_pk_bf16_f32 v5, v14, v16
	s_waitcnt lgkmcnt(2)
	v_cvt_pk_bf16_f32 v6, v18, v20
	s_waitcnt lgkmcnt(0)
	v_cvt_pk_bf16_f32 v7, v22, v24
	v_or3_b32 v8, v9, v8, v132
	global_store_dwordx4 v8, v[4:7], s[8:9]
	v_add_u32_e32 v8, 40, v26
	v_and_or_b32 v9, v8, s74, v135
	v_lshrrev_b32_e32 v9, 3, v9
	v_and_or_b32 v9, v9, 14, v131
	v_lshlrev_b32_e32 v8, 6, v8
	v_and_b32_e32 v8, 0xc0, v8
	v_lshlrev_b32_e32 v9, 10, v9
	v_cvt_pk_bf16_f32 v4, v11, v13
	v_cvt_pk_bf16_f32 v5, v15, v17
	v_cvt_pk_bf16_f32 v6, v19, v21
	v_cvt_pk_bf16_f32 v7, v23, v25
	v_or3_b32 v24, v9, v8, v132
	ds_read2_b32 v[8:9], v134 offset0:48 offset1:56
	ds_read2_b32 v[10:11], v134 offset0:113 offset1:121
	ds_read2_b32 v[12:13], v134 offset0:178 offset1:186
	ds_read2_b32 v[14:15], v134 offset0:243 offset1:251
	ds_read2_b32 v[16:17], v157 offset0:52 offset1:60
	ds_read2_b32 v[18:19], v157 offset0:117 offset1:125
	ds_read2_b32 v[20:21], v157 offset0:182 offset1:190
	ds_read2_b32 v[22:23], v157 offset0:247 offset1:255
	global_store_dwordx4 v24, v[4:7], s[8:9] offset:256
	v_mov_b32_e32 v25, v3
	s_waitcnt lgkmcnt(6)
	v_cvt_pk_bf16_f32 v4, v8, v10
	v_add_u32_e32 v8, 48, v26
	v_and_or_b32 v10, v8, s74, v135
	v_lshrrev_b32_e32 v10, 3, v10
	v_and_or_b32 v10, v10, 14, v131
	v_lshlrev_b32_e32 v8, 6, v8
	v_and_b32_e32 v8, 0xc0, v8
	v_lshlrev_b32_e32 v10, 10, v10
	v_or3_b32 v8, v10, v8, v132
	v_xor_b32_e32 v24, 32, v8
	s_waitcnt lgkmcnt(4)
	v_cvt_pk_bf16_f32 v5, v12, v14
	s_waitcnt lgkmcnt(2)
	v_cvt_pk_bf16_f32 v6, v16, v18
	s_waitcnt lgkmcnt(0)
	v_cvt_pk_bf16_f32 v7, v20, v22
	v_lshl_add_u64 v[24:25], s[8:9], 0, v[24:25]
	v_add_u32_e32 v8, 56, v26
	global_store_dwordx4 v[24:25], v[4:7], off offset:512
	s_nop 1
	v_cvt_pk_bf16_f32 v4, v9, v11
	v_and_or_b32 v9, v8, s74, v133
	v_lshrrev_b32_e32 v9, 3, v9
	v_and_or_b32 v9, v9, 14, v131
	v_lshlrev_b32_e32 v8, 6, v8
	v_and_b32_e32 v8, 0xc0, v8
	v_lshlrev_b32_e32 v9, 10, v9
	v_or3_b32 v8, v9, v8, v132
	v_xor_b32_e32 v8, 32, v8
	v_mov_b32_e32 v9, v3
	v_cvt_pk_bf16_f32 v5, v13, v15
	v_cvt_pk_bf16_f32 v6, v17, v19
	v_cvt_pk_bf16_f32 v7, v21, v23
	v_lshl_add_u64 v[8:9], s[8:9], 0, v[8:9]
	global_store_dwordx4 v[8:9], v[4:7], off offset:768
	s_waitcnt lgkmcnt(0)

; __device__ __forceinline__ void phase0(const Args& a, LAS unsigned char* lds, int bid, int G) {
;     ...
;     for (int m = gw; m < T; m += NGW) {
;         const f32x4* xr = (const f32x4*)(a.x + (size_t)m * DM) + lane;
;         f32x4 v[16]; float s = 0.f;
; #pragma unroll
;         for (int j = 0; j < 16; ++j) { v[j] = xr[64 * j]; s += (v[j][0] * v[j][0] + v[j][1] * v[j][1]) + (v[j][2] * v[j][2] + v[j][3] * v[j][3]); }
;         const float rstd = 1.0f / sqrtf(wave_sum(s) * (1.0f / DM) + EPS);
.LBB0_50:
	global_load_dwordx4 v[12:15], v[92:93], off nt
	global_load_dwordx4 v[8:11], v[92:93], off offset:1024 nt
	global_load_dwordx4 v[4:7], v[92:93], off offset:2048 nt
	global_load_dwordx4 v[0:3], v[92:93], off offset:3072 nt
	v_add_co_u32_e32 v94, vcc, s7, v92
	s_lshr_b32 s0, s76, 3
	s_nop 0
	v_addc_co_u32_e32 v95, vcc, 0, v93, vcc
	v_add_co_u32_e32 v96, vcc, s12, v92
	s_ashr_i32 s15, s76, 1
	s_nop 0
	v_addc_co_u32_e32 v97, vcc, 0, v93, vcc
	v_add_co_u32_e32 v98, vcc, s13, v92
	s_and_b32 s1, s10, 0x3c0
	s_nop 0
	v_addc_co_u32_e32 v99, vcc, 0, v93, vcc
	global_load_dwordx4 v[112:115], v[66:67], off
	global_load_dwordx4 v[60:63], v[96:97], off offset:-4096 nt
	global_load_dwordx4 v[52:55], v[94:95], off offset:2048 nt
	global_load_dwordx4 v[56:59], v[94:95], off offset:1024 nt
	global_load_dwordx4 v[48:51], v[94:95], off offset:3072 nt
	global_load_dwordx4 v[40:43], v[96:97], off offset:1024 nt
	global_load_dwordx4 v[44:47], v[96:97], off nt
	global_load_dwordx4 v[36:39], v[96:97], off offset:2048 nt
	global_load_dwordx4 v[28:31], v[98:99], off nt
	global_load_dwordx4 v[32:35], v[96:97], off offset:3072 nt
	global_load_dwordx4 v[24:27], v[98:99], off offset:1024 nt
	global_load_dwordx4 v[16:19], v[98:99], off offset:3072 nt
	global_load_dwordx4 v[20:23], v[98:99], off offset:2048 nt
	s_lshr_b32 s16, s10, 4
	v_and_or_b32 v64, s0, 14, v106
	s_andn2_b32 s15, s15, 63
	v_or_b32_e32 v94, s1, v107
	s_and_b32 s0, s16, 32
	v_lshlrev_b32_e32 v64, 10, v64
	v_or_b32_e32 v96, s15, v108
	v_bitop3_b32 v64, v94, v64, s0 bitop3:0xde
	v_ashrrev_i32_e32 v97, 31, v96
	v_lshl_add_u64 v[94:95], s[30:31], 0, v[64:65]
	v_lshlrev_b64 v[98:99], 14, v[96:97]
	v_lshl_add_u64 v[98:99], v[94:95], 0, v[98:99]
	s_add_i32 s76, s76, s6
	s_add_i32 s10, s10, s11
	v_lshl_add_u64 v[92:93], v[92:93], 0, s[8:9]
	s_cmpk_gt_i32 s76, 0x3fff
	s_waitcnt vmcnt(16)
	v_pk_mul_f32 v[116:117], v[14:15], v[14:15]
	v_pk_mul_f32 v[118:119], v[12:13], v[12:13]
	s_waitcnt vmcnt(15)
	v_pk_mul_f32 v[120:121], v[10:11], v[10:11]
	v_pk_mul_f32 v[122:123], v[8:9], v[8:9]
	v_pk_mov_b32 v[126:127], v[118:119], v[116:117] op_sel:[1,0]
	v_mov_b32_e32 v119, v117
	v_pk_mov_b32 v[116:117], v[122:123], v[120:121] op_sel:[1,0]
	v_mov_b32_e32 v123, v121
	s_waitcnt vmcnt(14)
	v_mul_f32_e32 v64, v5, v5
	v_mul_f32_e32 v124, v7, v7
	v_pk_add_f32 v[118:119], v[126:127], v[118:119]
	v_pk_add_f32 v[116:117], v[116:117], v[122:123]
	s_waitcnt vmcnt(13)
	v_mul_f32_e32 v97, v0, v0
	v_mul_f32_e32 v157, v1, v1
	v_mul_f32_e32 v133, v2, v2
	v_mul_f32_e32 v139, v3, v3
	v_pk_fma_f32 v[120:121], v[4:5], v[4:5], v[64:65] op_sel_hi:[1,1,0]
	v_pk_fma_f32 v[124:125], v[6:7], v[6:7], v[124:125] op_sel_hi:[1,1,0]
	v_pk_add_f32 v[118:119], v[118:119], v[118:119] op_sel:[0,1] op_sel_hi:[1,0]
	v_pk_add_f32 v[116:117], v[116:117], v[116:117] op_sel:[0,1] op_sel_hi:[1,0]
	s_waitcnt vmcnt(11)
	v_pk_mul_f32 v[128:129], v[62:63], v[62:63]
	v_pk_mul_f32 v[130:131], v[60:61], v[60:61]
	v_mov_b32_e32 v121, v133
	v_mov_b32_e32 v125, v139
	v_mov_b32_e32 v119, v97
	v_mov_b32_e32 v117, v157
	v_pk_mov_b32 v[122:123], v[130:131], v[128:129] op_sel:[1,0]
	v_mov_b32_e32 v131, v129
	v_pk_add_f32 v[120:121], v[120:121], v[124:125]
	v_pk_add_f32 v[116:117], v[118:119], v[116:117]
	s_waitcnt vmcnt(9)
	v_mul_f32_e32 v64, v57, v57
	v_mul_f32_e32 v132, v59, v59
	v_pk_add_f32 v[122:123], v[122:123], v[130:131]
	v_pk_add_f32 v[116:117], v[116:117], v[120:121]
	v_mul_f32_e32 v158, v52, v52
	v_mul_f32_e32 v159, v53, v53
	v_mul_f32_e32 v160, v54, v54
	v_mul_f32_e32 v161, v55, v55
	v_pk_fma_f32 v[126:127], v[56:57], v[56:57], v[64:65] op_sel_hi:[1,1,0]
	v_pk_fma_f32 v[128:129], v[58:59], v[58:59], v[132:133] op_sel_hi:[1,1,0]
	v_pk_add_f32 v[122:123], v[122:123], v[122:123] op_sel:[0,1] op_sel_hi:[1,0]
	v_pk_add_f32 v[116:117], v[116:117], v[116:117] op_sel:[0,1] op_sel_hi:[1,0]
	s_waitcnt vmcnt(8)
	v_pk_mul_f32 v[134:135], v[50:51], v[50:51]
	v_pk_mul_f32 v[136:137], v[48:49], v[48:49]
	v_mov_b32_e32 v127, v160
	v_mov_b32_e32 v129, v161
	v_mov_b32_e32 v123, v159
	v_mov_b32_e32 v117, v158
	v_pk_mov_b32 v[132:133], v[136:137], v[134:135] op_sel:[1,0]
	v_mov_b32_e32 v137, v135
	v_pk_add_f32 v[126:127], v[126:127], v[128:129]
	v_pk_add_f32 v[116:117], v[116:117], v[122:123]
	s_waitcnt vmcnt(6)
	v_mul_f32_e32 v138, v45, v45
	v_mul_f32_e32 v140, v47, v47
	v_pk_add_f32 v[124:125], v[132:133], v[136:137]
	v_pk_add_f32 v[116:117], v[116:117], v[126:127]
	v_mul_f32_e32 v162, v40, v40
	v_mul_f32_e32 v163, v41, v41
	v_mul_f32_e32 v164, v42, v42
	v_mul_f32_e32 v165, v43, v43
	v_pk_fma_f32 v[134:135], v[44:45], v[44:45], v[138:139] op_sel_hi:[1,1,0]
	v_pk_fma_f32 v[138:139], v[46:47], v[46:47], v[140:141] op_sel_hi:[1,1,0]
	v_pk_add_f32 v[124:125], v[124:125], v[124:125] op_sel:[0,1] op_sel_hi:[1,0]
	v_pk_add_f32 v[116:117], v[116:117], v[116:117] op_sel:[0,1] op_sel_hi:[1,0]
	s_waitcnt vmcnt(5)
	v_pk_mul_f32 v[142:143], v[38:39], v[38:39]
	v_pk_mul_f32 v[144:145], v[36:37], v[36:37]
	v_mov_b32_e32 v135, v164
	v_mov_b32_e32 v139, v165
	v_mov_b32_e32 v125, v163
	v_mov_b32_e32 v117, v162
	v_pk_mov_b32 v[140:141], v[144:145], v[142:143] op_sel:[1,0]
	v_mov_b32_e32 v145, v143
	v_pk_add_f32 v[128:129], v[134:135], v[138:139]
	v_pk_add_f32 v[116:117], v[116:117], v[124:125]
	s_waitcnt vmcnt(3)
	v_mul_f32_e32 v146, v33, v33
	v_mul_f32_e32 v148, v35, v35
	v_pk_add_f32 v[130:131], v[140:141], v[144:145]
	v_pk_add_f32 v[116:117], v[116:117], v[128:129]
	v_mul_f32_e32 v166, v28, v28
	v_mul_f32_e32 v167, v29, v29
	v_mul_f32_e32 v168, v30, v30
	v_mul_f32_e32 v169, v31, v31
	v_pk_fma_f32 v[142:143], v[32:33], v[32:33], v[146:147] op_sel_hi:[1,1,0]
	v_pk_fma_f32 v[146:147], v[34:35], v[34:35], v[148:149] op_sel_hi:[1,1,0]
	v_pk_add_f32 v[130:131], v[130:131], v[130:131] op_sel:[0,1] op_sel_hi:[1,0]
	v_pk_add_f32 v[116:117], v[116:117], v[116:117] op_sel:[0,1] op_sel_hi:[1,0]
	s_waitcnt vmcnt(2)
; __device__ __forceinline__ unsigned pk2(float lo, float hi) { return __builtin_bit_cast(unsigned, __builtin_convertvector((f32x2){lo, hi}, bf16x2_t)); }
; __device__ __forceinline__ void phase0(const Args& a, LAS unsigned char* lds, int bid, int G) {
;     ...
;         for (int j = 0; j < 16; ++j) { v[j] = xr[64 * j]; s += (v[j][0] * v[j][0] + v[j][1] * v[j][1]) + (v[j][2] * v[j][2] + v[j][3] * v[j][3]); }
;         const float rstd = 1.0f / sqrtf(wave_sum(s) * (1.0f / DM) + EPS);
;         char* xo = (char*)XN;
; #pragma unroll
;         for (int j = 0; j < 16; ++j) { const f32x4 w = *((const f32x4*)a.norm_w + lane + 64 * j);
;             u32x2 p; p.x = pk2(v[j][0] * rstd * w[0], v[j][1] * rstd * w[1]); p.y = pk2(v[j][2] * rstd * w[2], v[j][3] * rstd * w[3]); *(u32x2*)(xo + tiled_off(m, 4 * lane + 256 * j)) = p; }
	v_pk_mul_f32 v[150:151], v[26:27], v[26:27]
	v_pk_mul_f32 v[152:153], v[24:25], v[24:25]
	v_mov_b32_e32 v143, v168
	v_mov_b32_e32 v147, v169
	v_mov_b32_e32 v131, v167
	v_mov_b32_e32 v117, v166
	v_pk_mov_b32 v[148:149], v[152:153], v[150:151] op_sel:[1,0]
	v_mov_b32_e32 v153, v151
	v_pk_add_f32 v[134:135], v[142:143], v[146:147]
	v_pk_add_f32 v[116:117], v[116:117], v[130:131]
	s_waitcnt vmcnt(0)
	v_mul_f32_e32 v154, v21, v21
	v_mul_f32_e32 v156, v23, v23
	v_pk_add_f32 v[132:133], v[148:149], v[152:153]
	v_pk_add_f32 v[116:117], v[116:117], v[134:135]
	v_mul_f32_e32 v170, v16, v16
	v_mul_f32_e32 v171, v17, v17
	v_mul_f32_e32 v172, v18, v18
	v_mul_f32_e32 v173, v19, v19
	v_pk_fma_f32 v[150:151], v[20:21], v[20:21], v[154:155] op_sel_hi:[1,1,0]
	v_pk_fma_f32 v[154:155], v[22:23], v[22:23], v[156:157] op_sel_hi:[1,1,0]
	v_pk_add_f32 v[132:133], v[132:133], v[132:133] op_sel:[0,1] op_sel_hi:[1,0]
	v_pk_add_f32 v[116:117], v[116:117], v[116:117] op_sel:[0,1] op_sel_hi:[1,0]
	v_mov_b32_e32 v151, v172
	v_mov_b32_e32 v155, v173
	v_mov_b32_e32 v133, v171
	v_mov_b32_e32 v117, v170
	v_pk_add_f32 v[136:137], v[150:151], v[154:155]
	v_pk_add_f32 v[116:117], v[116:117], v[132:133]
	s_nop 0
	v_pk_add_f32 v[116:117], v[116:117], v[136:137]
	s_nop 0
	v_add_f32_e32 v64, v116, v117
	ds_bpermute_b32 v97, v100, v64
	s_waitcnt lgkmcnt(0)
	v_add_f32_e32 v64, v64, v97
	ds_bpermute_b32 v97, v101, v64
	s_waitcnt lgkmcnt(0)
	v_add_f32_e32 v64, v64, v97
	ds_bpermute_b32 v97, v102, v64
	s_waitcnt lgkmcnt(0)
	v_add_f32_e32 v64, v64, v97
	ds_bpermute_b32 v97, v103, v64
	s_waitcnt lgkmcnt(0)
	v_add_f32_e32 v64, v64, v97
	ds_bpermute_b32 v97, v104, v64
	s_waitcnt lgkmcnt(0)
	v_add_f32_e32 v64, v64, v97
	ds_bpermute_b32 v97, v105, v64
	s_waitcnt lgkmcnt(0)
	v_add_f32_e32 v64, v64, v97
	v_fmamk_f32 v64, v64, 0x39800000, v110
	v_mul_f32_e32 v97, 0x4f800000, v64
	v_cmp_gt_f32_e32 vcc, s14, v64
	s_nop 1
	v_cndmask_b32_e32 v64, v64, v97, vcc
	v_sqrt_f32_e32 v97, v64
	s_nop 0
	v_add_u32_e32 v116, -1, v97
	v_add_u32_e32 v117, 1, v97
	v_fma_f32 v118, -v116, v97, v64
	v_fma_f32 v119, -v117, v97, v64
	v_cmp_ge_f32_e64 s[0:1], 0, v118
	s_nop 1
	v_cndmask_b32_e64 v97, v97, v116, s[0:1]
	v_cmp_lt_f32_e64 s[0:1], 0, v119
	s_nop 1
	v_cndmask_b32_e64 v97, v97, v117, s[0:1]
	v_mul_f32_e32 v116, 0x37800000, v97
	v_cndmask_b32_e32 v97, v97, v116, vcc
	v_cmp_class_f32_e32 vcc, v64, v111
	s_nop 1
	v_cndmask_b32_e32 v64, v97, v64, vcc
	v_div_scale_f32 v97, s[0:1], v64, v64, 1.0
	v_rcp_f32_e32 v117, v97
	v_div_scale_f32 v116, vcc, 1.0, v64, 1.0
	v_fma_f32 v118, -v97, v117, 1.0
	v_fmac_f32_e32 v117, v118, v117
	v_mul_f32_e32 v118, v116, v117
	v_fma_f32 v119, -v97, v118, v116
	v_fmac_f32_e32 v118, v119, v117
	v_fma_f32 v97, -v97, v118, v116
	v_div_fmas_f32 v97, v97, v117, v118
	v_div_fixup_f32 v64, v97, v64, 1.0
	v_pk_mul_f32 v[12:13], v[12:13], v[64:65] op_sel_hi:[1,0]
	v_pk_mul_f32 v[14:15], v[14:15], v[64:65] op_sel_hi:[1,0]
	v_pk_mul_f32 v[12:13], v[112:113], v[12:13]
	v_pk_mul_f32 v[14:15], v[114:115], v[14:15]
	v_cvt_pk_bf16_f32 v12, v12, v13
	v_cvt_pk_bf16_f32 v13, v14, v15
	global_store_dwordx2 v[98:99], v[12:13], off
	global_load_dwordx4 v[12:15], v[66:67], off offset:1024
	v_or_b32_e32 v98, 4, v96
	v_ashrrev_i32_e32 v99, 31, v98
	v_pk_mul_f32 v[8:9], v[8:9], v[64:65] op_sel_hi:[1,0]
	v_pk_mul_f32 v[10:11], v[10:11], v[64:65] op_sel_hi:[1,0]
	v_lshlrev_b64 v[98:99], 14, v[98:99]
	v_lshl_add_u64 v[98:99], v[94:95], 0, v[98:99]
	v_pk_mul_f32 v[4:5], v[4:5], v[64:65] op_sel_hi:[1,0]
	v_pk_mul_f32 v[6:7], v[6:7], v[64:65] op_sel_hi:[1,0]
	v_pk_mul_f32 v[0:1], v[0:1], v[64:65] op_sel_hi:[1,0]
	v_pk_mul_f32 v[2:3], v[2:3], v[64:65] op_sel_hi:[1,0]
	s_waitcnt vmcnt(0)
	v_pk_mul_f32 v[8:9], v[12:13], v[8:9]
	v_pk_mul_f32 v[10:11], v[14:15], v[10:11]
	v_cvt_pk_bf16_f32 v8, v8, v9
	v_cvt_pk_bf16_f32 v9, v10, v11
	global_store_dwordx2 v[98:99], v[8:9], off
	global_load_dwordx4 v[8:11], v[66:67], off offset:2048
	v_or_b32_e32 v12, 8, v96
	v_ashrrev_i32_e32 v13, 31, v12
	v_lshlrev_b64 v[12:13], 14, v[12:13]
	v_lshl_add_u64 v[12:13], v[94:95], 0, v[12:13]
	s_waitcnt vmcnt(0)
	v_pk_mul_f32 v[4:5], v[8:9], v[4:5]
	v_pk_mul_f32 v[6:7], v[10:11], v[6:7]
	v_cvt_pk_bf16_f32 v4, v4, v5
	v_cvt_pk_bf16_f32 v5, v6, v7
	global_store_dwordx2 v[12:13], v[4:5], off
	global_load_dwordx4 v[4:7], v[66:67], off offset:3072
	v_or_b32_e32 v8, 12, v96
	v_ashrrev_i32_e32 v9, 31, v8
	v_lshlrev_b64 v[8:9], 14, v[8:9]
	v_lshl_add_u64 v[8:9], v[94:95], 0, v[8:9]
	s_waitcnt vmcnt(0)
	v_pk_mul_f32 v[0:1], v[4:5], v[0:1]
	v_pk_mul_f32 v[2:3], v[6:7], v[2:3]
	v_cvt_pk_bf16_f32 v0, v0, v1
	v_cvt_pk_bf16_f32 v1, v2, v3
	global_store_dwordx2 v[8:9], v[0:1], off
	global_load_dwordx4 v[0:3], v[68:69], off
	v_or_b32_e32 v4, 16, v96
	v_ashrrev_i32_e32 v5, 31, v4
	v_pk_mul_f32 v[6:7], v[60:61], v[64:65] op_sel_hi:[1,0]
	v_pk_mul_f32 v[8:9], v[62:63], v[64:65] op_sel_hi:[1,0]
	v_lshlrev_b64 v[4:5], 14, v[4:5]
	v_lshl_add_u64 v[4:5], v[94:95], 0, v[4:5]
	s_waitcnt vmcnt(0)
	v_pk_mul_f32 v[0:1], v[0:1], v[6:7]
	v_pk_mul_f32 v[2:3], v[2:3], v[8:9]
	v_cvt_pk_bf16_f32 v0, v0, v1
	v_cvt_pk_bf16_f32 v1, v2, v3
	global_store_dwordx2 v[4:5], v[0:1], off
	global_load_dwordx4 v[0:3], v[70:71], off
	v_or_b32_e32 v4, 20, v96
	v_ashrrev_i32_e32 v5, 31, v4
	v_pk_mul_f32 v[6:7], v[56:57], v[64:65] op_sel_hi:[1,0]
	v_pk_mul_f32 v[8:9], v[58:59], v[64:65] op_sel_hi:[1,0]
	v_lshlrev_b64 v[4:5], 14, v[4:5]
	v_lshl_add_u64 v[4:5], v[94:95], 0, v[4:5]
	s_waitcnt vmcnt(0)
; __device__ __forceinline__ unsigned pk2(float lo, float hi) { return __builtin_bit_cast(unsigned, __builtin_convertvector((f32x2){lo, hi}, bf16x2_t)); }
; __device__ __forceinline__ void phase0(const Args& a, LAS unsigned char* lds, int bid, int G) {
;     ...
;         for (int j = 0; j < 16; ++j) { const f32x4 w = *((const f32x4*)a.norm_w + lane + 64 * j);
;             u32x2 p; p.x = pk2(v[j][0] * rstd * w[0], v[j][1] * rstd * w[1]); p.y = pk2(v[j][2] * rstd * w[2], v[j][3] * rstd * w[3]); *(u32x2*)(xo + tiled_off(m, 4 * lane + 256 * j)) = p; }
	v_pk_mul_f32 v[0:1], v[6:7], v[0:1]
	v_pk_mul_f32 v[2:3], v[8:9], v[2:3]
	v_cvt_pk_bf16_f32 v0, v0, v1
	v_cvt_pk_bf16_f32 v1, v2, v3
	global_store_dwordx2 v[4:5], v[0:1], off
	global_load_dwordx4 v[0:3], v[72:73], off
	v_or_b32_e32 v4, 24, v96
	v_ashrrev_i32_e32 v5, 31, v4
	v_pk_mul_f32 v[6:7], v[52:53], v[64:65] op_sel_hi:[1,0]
	v_pk_mul_f32 v[8:9], v[54:55], v[64:65] op_sel_hi:[1,0]
	v_lshlrev_b64 v[4:5], 14, v[4:5]
	v_lshl_add_u64 v[4:5], v[94:95], 0, v[4:5]
	s_waitcnt vmcnt(0)
	v_pk_mul_f32 v[0:1], v[6:7], v[0:1]
	v_pk_mul_f32 v[2:3], v[8:9], v[2:3]
	v_cvt_pk_bf16_f32 v0, v0, v1
	v_cvt_pk_bf16_f32 v1, v2, v3
	global_store_dwordx2 v[4:5], v[0:1], off
	global_load_dwordx4 v[0:3], v[74:75], off
	v_or_b32_e32 v4, 28, v96
	v_ashrrev_i32_e32 v5, 31, v4
	v_pk_mul_f32 v[6:7], v[48:49], v[64:65] op_sel_hi:[1,0]
	v_pk_mul_f32 v[8:9], v[50:51], v[64:65] op_sel_hi:[1,0]
	v_lshlrev_b64 v[4:5], 14, v[4:5]
	v_lshl_add_u64 v[4:5], v[94:95], 0, v[4:5]
	s_waitcnt vmcnt(0)
	v_pk_mul_f32 v[0:1], v[6:7], v[0:1]
	v_pk_mul_f32 v[2:3], v[8:9], v[2:3]
	v_cvt_pk_bf16_f32 v0, v0, v1
	v_cvt_pk_bf16_f32 v1, v2, v3
	global_store_dwordx2 v[4:5], v[0:1], off
	global_load_dwordx4 v[0:3], v[76:77], off
	v_or_b32_e32 v4, 32, v96
	v_ashrrev_i32_e32 v5, 31, v4
	v_pk_mul_f32 v[6:7], v[44:45], v[64:65] op_sel_hi:[1,0]
	v_pk_mul_f32 v[8:9], v[46:47], v[64:65] op_sel_hi:[1,0]
	v_lshlrev_b64 v[4:5], 14, v[4:5]
	v_lshl_add_u64 v[4:5], v[94:95], 0, v[4:5]
	s_waitcnt vmcnt(0)
	v_pk_mul_f32 v[0:1], v[6:7], v[0:1]
	v_pk_mul_f32 v[2:3], v[8:9], v[2:3]
	v_cvt_pk_bf16_f32 v0, v0, v1
	v_cvt_pk_bf16_f32 v1, v2, v3
	global_store_dwordx2 v[4:5], v[0:1], off
	global_load_dwordx4 v[0:3], v[78:79], off
	v_or_b32_e32 v4, 36, v96
	v_ashrrev_i32_e32 v5, 31, v4
	v_pk_mul_f32 v[6:7], v[40:41], v[64:65] op_sel_hi:[1,0]
	v_pk_mul_f32 v[8:9], v[42:43], v[64:65] op_sel_hi:[1,0]
	v_lshlrev_b64 v[4:5], 14, v[4:5]
	v_lshl_add_u64 v[4:5], v[94:95], 0, v[4:5]
	s_waitcnt vmcnt(0)
	v_pk_mul_f32 v[0:1], v[6:7], v[0:1]
	v_pk_mul_f32 v[2:3], v[8:9], v[2:3]
	v_cvt_pk_bf16_f32 v0, v0, v1
	v_cvt_pk_bf16_f32 v1, v2, v3
	global_store_dwordx2 v[4:5], v[0:1], off
	global_load_dwordx4 v[0:3], v[80:81], off
	v_or_b32_e32 v4, 40, v96
	v_ashrrev_i32_e32 v5, 31, v4
	v_pk_mul_f32 v[6:7], v[36:37], v[64:65] op_sel_hi:[1,0]
	v_pk_mul_f32 v[8:9], v[38:39], v[64:65] op_sel_hi:[1,0]
	v_lshlrev_b64 v[4:5], 14, v[4:5]
	v_lshl_add_u64 v[4:5], v[94:95], 0, v[4:5]
	s_waitcnt vmcnt(0)
	v_pk_mul_f32 v[0:1], v[6:7], v[0:1]
	v_pk_mul_f32 v[2:3], v[8:9], v[2:3]
	v_cvt_pk_bf16_f32 v0, v0, v1
	v_cvt_pk_bf16_f32 v1, v2, v3
	global_store_dwordx2 v[4:5], v[0:1], off
	global_load_dwordx4 v[0:3], v[82:83], off
	v_or_b32_e32 v4, 44, v96
	v_ashrrev_i32_e32 v5, 31, v4
	v_pk_mul_f32 v[6:7], v[32:33], v[64:65] op_sel_hi:[1,0]
	v_pk_mul_f32 v[8:9], v[34:35], v[64:65] op_sel_hi:[1,0]
	v_lshlrev_b64 v[4:5], 14, v[4:5]
	v_lshl_add_u64 v[4:5], v[94:95], 0, v[4:5]
	s_waitcnt vmcnt(0)
	v_pk_mul_f32 v[0:1], v[6:7], v[0:1]
	v_pk_mul_f32 v[2:3], v[8:9], v[2:3]
	v_cvt_pk_bf16_f32 v0, v0, v1
	v_cvt_pk_bf16_f32 v1, v2, v3
	global_store_dwordx2 v[4:5], v[0:1], off
	global_load_dwordx4 v[0:3], v[84:85], off
	v_or_b32_e32 v4, 48, v96
	v_ashrrev_i32_e32 v5, 31, v4
	v_pk_mul_f32 v[6:7], v[28:29], v[64:65] op_sel_hi:[1,0]
	v_pk_mul_f32 v[8:9], v[30:31], v[64:65] op_sel_hi:[1,0]
	v_lshlrev_b64 v[4:5], 14, v[4:5]
	v_lshl_add_u64 v[4:5], v[94:95], 0, v[4:5]
	s_waitcnt vmcnt(0)
	v_pk_mul_f32 v[0:1], v[6:7], v[0:1]
	v_pk_mul_f32 v[2:3], v[8:9], v[2:3]
	v_cvt_pk_bf16_f32 v0, v0, v1
	v_cvt_pk_bf16_f32 v1, v2, v3
	global_store_dwordx2 v[4:5], v[0:1], off
	global_load_dwordx4 v[0:3], v[86:87], off
	v_or_b32_e32 v4, 52, v96
	v_ashrrev_i32_e32 v5, 31, v4
	v_pk_mul_f32 v[6:7], v[24:25], v[64:65] op_sel_hi:[1,0]
	v_pk_mul_f32 v[8:9], v[26:27], v[64:65] op_sel_hi:[1,0]
	v_lshlrev_b64 v[4:5], 14, v[4:5]
	v_lshl_add_u64 v[4:5], v[94:95], 0, v[4:5]
	s_waitcnt vmcnt(0)
	v_pk_mul_f32 v[0:1], v[6:7], v[0:1]
	v_pk_mul_f32 v[2:3], v[8:9], v[2:3]
	v_cvt_pk_bf16_f32 v0, v0, v1
	v_cvt_pk_bf16_f32 v1, v2, v3
	global_store_dwordx2 v[4:5], v[0:1], off
	global_load_dwordx4 v[0:3], v[88:89], off
	v_or_b32_e32 v4, 56, v96
	v_ashrrev_i32_e32 v5, 31, v4
	v_pk_mul_f32 v[6:7], v[20:21], v[64:65] op_sel_hi:[1,0]
	v_pk_mul_f32 v[8:9], v[22:23], v[64:65] op_sel_hi:[1,0]
	v_lshlrev_b64 v[4:5], 14, v[4:5]
	v_lshl_add_u64 v[4:5], v[94:95], 0, v[4:5]
	s_waitcnt vmcnt(0)
	v_pk_mul_f32 v[0:1], v[6:7], v[0:1]
	v_pk_mul_f32 v[2:3], v[8:9], v[2:3]
	v_cvt_pk_bf16_f32 v0, v0, v1
	v_cvt_pk_bf16_f32 v1, v2, v3
	global_store_dwordx2 v[4:5], v[0:1], off
	global_load_dwordx4 v[0:3], v[90:91], off
	v_or_b32_e32 v4, s15, v109
	v_ashrrev_i32_e32 v5, 31, v4
	v_pk_mul_f32 v[6:7], v[16:17], v[64:65] op_sel_hi:[1,0]
	v_pk_mul_f32 v[8:9], v[18:19], v[64:65] op_sel_hi:[1,0]
	v_lshlrev_b64 v[4:5], 14, v[4:5]
	v_lshl_add_u64 v[4:5], v[94:95], 0, v[4:5]
	s_waitcnt vmcnt(0)
	v_pk_mul_f32 v[0:1], v[6:7], v[0:1]
	v_pk_mul_f32 v[2:3], v[8:9], v[2:3]
	v_cvt_pk_bf16_f32 v0, v0, v1
	v_cvt_pk_bf16_f32 v1, v2, v3
	global_store_dwordx2 v[4:5], v[0:1], off
	s_cbranch_scc0 .LBB0_50
